# G1/G3: next unit's As[1][1] K-tile-1 staging moved ahead of the epilogue stores; the peeled iteration's first three counted waits leave the stores in flight
# speedup vs baseline: 1.0057x; 1.0011x over previous
.LBB0_117:
	s_ashr_i32 s13, s12, 31
	s_lshl_b64 s[16:17], s[12:13], 19
	s_add_u32 s16, s30, s16
	s_addc_u32 s17, s31, s17
	s_and_b64 s[18:19], s[2:3], exec
	s_cselect_b32 s13, s17, s21
	s_cselect_b32 s37, s16, s20
	s_ashr_i32 s11, s10, 31
	s_lshl_b64 s[18:19], s[10:11], 19
	s_add_u32 s18, s28, s18
	s_addc_u32 s19, s29, s19
	s_and_b64 s[24:25], s[2:3], exec
	s_cselect_b32 s11, s19, s23
	s_cselect_b32 s38, s18, s22
	s_add_u32 s20, s20, 0x40080
	s_addc_u32 s21, s21, 0
	s_add_u32 s39, s22, 0x100
	s_addc_u32 s40, s23, 0
	s_mov_b32 s41, -2
	ds_read_b128 v[170:173], v162
	ds_read_b128 v[174:177], v162 offset:1024
	ds_read_b128 v[178:181], v162 offset:2048
	ds_read_b128 v[182:185], v162 offset:3072
	ds_read_b128 v[186:189], v163
	ds_read_b128 v[190:193], v163 offset:1024
	ds_read_b128 v[194:197], v163 offset:2048
	ds_read_b128 v[198:201], v163 offset:3072
	s_add_u32 s22, s20, 0xfffc0080
	s_addc_u32 s23, s21, -1
	s_cmp_eq_u32 s41, 12
	s_cselect_b32 s25, s13, s23
	s_cselect_b32 s24, s37, s22
	s_cselect_b32 s23, s11, s40
	s_cselect_b32 s22, s38, s39
	v_readfirstlane_b32 s42, v165
	v_lshl_add_u64 v[226:227], s[20:21], 0, v[136:137]
	s_mov_b32 m0, s42
	v_readfirstlane_b32 s42, v166
	ds_read_b128 v[202:205], v164
	ds_read_b128 v[206:209], v164 offset:1024
	ds_read_b128 v[210:213], v164 offset:2048
	ds_read_b128 v[214:217], v164 offset:3072
	ds_read_b128 v[218:221], v164 offset:4096
	ds_read_b128 v[222:225], v164 offset:5120
	ds_read_b128 v[230:233], v164 offset:6144
	ds_read_b128 v[234:237], v164 offset:7168
	s_cmp_lg_u32 s15, 1
	s_cbranch_scc1 .Lpeel_st_g1l0
	global_load_lds_dwordx4 v[226:227], off
	v_lshl_add_u64 v[226:227], s[20:21], 0, v[138:139]
	s_mov_b32 m0, s42
	s_nop 0
	global_load_lds_dwordx4 v[226:227], off
.Lpeel_st_g1l0:
	s_waitcnt vmcnt(24)
	s_waitcnt lgkmcnt(0)
	s_barrier
	s_setprio 1
	s_waitcnt lgkmcnt(0)
	v_mfma_f32_16x16x32_bf16 v[124:127], v[170:173], v[202:205], 0
	v_mfma_f32_16x16x32_bf16 v[120:123], v[178:181], v[202:205], 0
	v_mfma_f32_16x16x32_bf16 v[116:119], v[170:173], v[210:213], 0
	v_mfma_f32_16x16x32_bf16 v[108:111], v[178:181], v[210:213], 0
	v_mfma_f32_16x16x32_bf16 v[100:103], v[170:173], v[218:221], 0
	v_mfma_f32_16x16x32_bf16 v[92:95], v[178:181], v[218:221], 0
	v_mfma_f32_16x16x32_bf16 v[84:87], v[170:173], v[230:233], 0
	v_mfma_f32_16x16x32_bf16 v[76:79], v[178:181], v[230:233], 0
	v_mfma_f32_16x16x32_bf16 v[124:127], v[174:177], v[206:209], v[124:127]
	v_mfma_f32_16x16x32_bf16 v[120:123], v[182:185], v[206:209], v[120:123]
	v_mfma_f32_16x16x32_bf16 v[116:119], v[174:177], v[214:217], v[116:119]
	v_mfma_f32_16x16x32_bf16 v[108:111], v[182:185], v[214:217], v[108:111]
	v_mfma_f32_16x16x32_bf16 v[100:103], v[174:177], v[222:225], v[100:103]
	v_mfma_f32_16x16x32_bf16 v[92:95], v[182:185], v[222:225], v[92:95]
	v_mfma_f32_16x16x32_bf16 v[84:87], v[174:177], v[234:237], v[84:87]
	v_mfma_f32_16x16x32_bf16 v[76:79], v[182:185], v[234:237], v[76:79]
	s_setprio 0
	s_setprio 1
	v_mfma_f32_16x16x32_bf16 v[112:115], v[186:189], v[202:205], 0
	v_mfma_f32_16x16x32_bf16 v[104:107], v[194:197], v[202:205], 0
	v_mfma_f32_16x16x32_bf16 v[96:99], v[186:189], v[210:213], 0
	v_mfma_f32_16x16x32_bf16 v[88:91], v[194:197], v[210:213], 0
	v_mfma_f32_16x16x32_bf16 v[80:83], v[186:189], v[218:221], 0
	v_mfma_f32_16x16x32_bf16 v[72:75], v[194:197], v[218:221], 0
	v_mfma_f32_16x16x32_bf16 v[68:71], v[186:189], v[230:233], 0
	v_mfma_f32_16x16x32_bf16 v[64:67], v[194:197], v[230:233], 0
	v_mfma_f32_16x16x32_bf16 v[112:115], v[190:193], v[206:209], v[112:115]
	v_mfma_f32_16x16x32_bf16 v[104:107], v[198:201], v[206:209], v[104:107]
	v_mfma_f32_16x16x32_bf16 v[96:99], v[190:193], v[214:217], v[96:99]
	v_mfma_f32_16x16x32_bf16 v[88:91], v[198:201], v[214:217], v[88:91]
	v_mfma_f32_16x16x32_bf16 v[80:83], v[190:193], v[222:225], v[80:83]
	v_mfma_f32_16x16x32_bf16 v[72:75], v[198:201], v[222:225], v[72:75]
	v_mfma_f32_16x16x32_bf16 v[68:71], v[190:193], v[234:237], v[68:71]
	v_mfma_f32_16x16x32_bf16 v[64:67], v[198:201], v[234:237], v[64:67]
	s_setprio 0
	s_barrier
	v_readfirstlane_b32 s42, v146
	v_lshl_add_u64 v[226:227], s[22:23], 0, v[130:131]
	s_mov_b32 m0, s42
	v_readfirstlane_b32 s42, v147
	ds_read_b128 v[202:205], v164 offset:16384
	ds_read_b128 v[206:209], v164 offset:17408
	ds_read_b128 v[210:213], v164 offset:18432
	ds_read_b128 v[214:217], v164 offset:19456
	ds_read_b128 v[218:221], v164 offset:20480
	ds_read_b128 v[222:225], v164 offset:21504
	ds_read_b128 v[230:233], v164 offset:22528
	ds_read_b128 v[234:237], v164 offset:23552
	global_load_lds_dwordx4 v[226:227], off
	s_mov_b32 m0, s42
	s_add_u32 s42, s22, 0x40000
	v_lshl_add_u64 v[238:239], s[22:23], 0, v[134:135]
	s_addc_u32 s43, s23, 0
	v_readfirstlane_b32 s44, v148
	global_load_lds_dwordx4 v[238:239], off
	v_lshl_add_u64 v[240:241], s[42:43], 0, v[130:131]
	s_mov_b32 m0, s44
	v_lshl_add_u64 v[242:243], s[24:25], 0, v[132:133]
	global_load_lds_dwordx4 v[240:241], off
	v_lshl_add_u64 v[240:241], s[42:43], 0, v[134:135]
	v_readfirstlane_b32 s42, v149
	s_mov_b32 m0, s42
	v_readfirstlane_b32 s42, v150
	global_load_lds_dwordx4 v[240:241], off
	v_lshl_add_u64 v[240:241], s[24:25], 0, v[128:129]
	s_mov_b32 m0, s42
	v_readfirstlane_b32 s42, v151
	global_load_lds_dwordx4 v[240:241], off
	s_mov_b32 m0, s42
	s_nop 0
	global_load_lds_dwordx4 v[242:243], off
	s_waitcnt vmcnt(24)
	s_cmp_lg_u32 s15, 1
	s_cbranch_scc1 .Lpeel_w2_g1l0
	s_waitcnt vmcnt(8)
.Lpeel_w2_g1l0:
	s_waitcnt lgkmcnt(0)
	s_barrier
	s_setprio 1
	s_waitcnt lgkmcnt(0)
	v_mfma_f32_16x16x32_bf16 v[60:63], v[170:173], v[202:205], 0
	v_mfma_f32_16x16x32_bf16 v[56:59], v[178:181], v[202:205], 0
	v_mfma_f32_16x16x32_bf16 v[52:55], v[170:173], v[210:213], 0
	v_mfma_f32_16x16x32_bf16 v[44:47], v[178:181], v[210:213], 0
	v_mfma_f32_16x16x32_bf16 v[36:39], v[170:173], v[218:221], 0
	v_mfma_f32_16x16x32_bf16 v[28:31], v[178:181], v[218:221], 0
	v_mfma_f32_16x16x32_bf16 v[20:23], v[170:173], v[230:233], 0
	v_mfma_f32_16x16x32_bf16 v[12:15], v[178:181], v[230:233], 0
	v_mfma_f32_16x16x32_bf16 v[60:63], v[174:177], v[206:209], v[60:63]
	v_mfma_f32_16x16x32_bf16 v[56:59], v[182:185], v[206:209], v[56:59]
	v_mfma_f32_16x16x32_bf16 v[52:55], v[174:177], v[214:217], v[52:55]
	v_mfma_f32_16x16x32_bf16 v[44:47], v[182:185], v[214:217], v[44:47]
	v_mfma_f32_16x16x32_bf16 v[36:39], v[174:177], v[222:225], v[36:39]
	v_mfma_f32_16x16x32_bf16 v[28:31], v[182:185], v[222:225], v[28:31]
	v_mfma_f32_16x16x32_bf16 v[20:23], v[174:177], v[234:237], v[20:23]
	v_mfma_f32_16x16x32_bf16 v[12:15], v[182:185], v[234:237], v[12:15]
	s_setprio 0
	s_setprio 1
	v_mfma_f32_16x16x32_bf16 v[48:51], v[186:189], v[202:205], 0
	v_mfma_f32_16x16x32_bf16 v[40:43], v[194:197], v[202:205], 0
	v_mfma_f32_16x16x32_bf16 v[32:35], v[186:189], v[210:213], 0
	v_mfma_f32_16x16x32_bf16 v[24:27], v[194:197], v[210:213], 0
	v_mfma_f32_16x16x32_bf16 v[16:19], v[186:189], v[218:221], 0
	v_mfma_f32_16x16x32_bf16 v[8:11], v[194:197], v[218:221], 0
	v_mfma_f32_16x16x32_bf16 v[4:7], v[186:189], v[230:233], 0
	v_mfma_f32_16x16x32_bf16 v[0:3], v[194:197], v[230:233], 0
	v_mfma_f32_16x16x32_bf16 v[48:51], v[190:193], v[206:209], v[48:51]
	v_mfma_f32_16x16x32_bf16 v[40:43], v[198:201], v[206:209], v[40:43]
	v_mfma_f32_16x16x32_bf16 v[32:35], v[190:193], v[214:217], v[32:35]
	v_mfma_f32_16x16x32_bf16 v[24:27], v[198:201], v[214:217], v[24:27]
	v_mfma_f32_16x16x32_bf16 v[16:19], v[190:193], v[222:225], v[16:19]
	v_mfma_f32_16x16x32_bf16 v[8:11], v[198:201], v[222:225], v[8:11]
	v_mfma_f32_16x16x32_bf16 v[4:7], v[190:193], v[234:237], v[4:7]
	v_mfma_f32_16x16x32_bf16 v[0:3], v[198:201], v[234:237], v[0:3]
	s_setprio 0
	s_barrier
	ds_read_b128 v[170:173], v167
	ds_read_b128 v[174:177], v167 offset:1024
	ds_read_b128 v[178:181], v167 offset:2048
	ds_read_b128 v[182:185], v167 offset:3072
	ds_read_b128 v[186:189], v168
	ds_read_b128 v[190:193], v168 offset:1024
	ds_read_b128 v[194:197], v168 offset:2048
	ds_read_b128 v[198:201], v168 offset:3072
	s_add_u32 s24, s24, 0x40000
	s_addc_u32 s25, s25, 0
	v_readfirstlane_b32 s42, v152
	v_lshl_add_u64 v[244:245], s[24:25], 0, v[128:129]
	s_mov_b32 m0, s42
	ds_read_b128 v[202:205], v164 offset:32768
	ds_read_b128 v[206:209], v164 offset:33792
	ds_read_b128 v[210:213], v164 offset:34816
	ds_read_b128 v[214:217], v164 offset:35840
	ds_read_b128 v[218:221], v164 offset:36864
	ds_read_b128 v[222:225], v164 offset:37888
	ds_read_b128 v[230:233], v164 offset:38912
	ds_read_b128 v[234:237], v164 offset:39936
	global_load_lds_dwordx4 v[244:245], off
	v_lshl_add_u64 v[244:245], s[24:25], 0, v[132:133]
	v_readfirstlane_b32 s24, v153
	s_mov_b32 m0, s24
	s_nop 0
	global_load_lds_dwordx4 v[244:245], off
	s_waitcnt vmcnt(24)
	s_cmp_lg_u32 s15, 1
	s_cbranch_scc1 .Lpeel_w3_g1l0
	s_waitcnt vmcnt(8)
.Lpeel_w3_g1l0:
	s_waitcnt lgkmcnt(0)
	s_barrier
	s_setprio 1
	s_waitcnt lgkmcnt(0)
	v_mfma_f32_16x16x32_bf16 v[124:127], v[170:173], v[202:205], v[124:127]
	v_mfma_f32_16x16x32_bf16 v[120:123], v[178:181], v[202:205], v[120:123]
	v_mfma_f32_16x16x32_bf16 v[116:119], v[170:173], v[210:213], v[116:119]
	v_mfma_f32_16x16x32_bf16 v[108:111], v[178:181], v[210:213], v[108:111]
	v_mfma_f32_16x16x32_bf16 v[100:103], v[170:173], v[218:221], v[100:103]
	v_mfma_f32_16x16x32_bf16 v[92:95], v[178:181], v[218:221], v[92:95]
	v_mfma_f32_16x16x32_bf16 v[84:87], v[170:173], v[230:233], v[84:87]
	v_mfma_f32_16x16x32_bf16 v[76:79], v[178:181], v[230:233], v[76:79]
	v_mfma_f32_16x16x32_bf16 v[124:127], v[174:177], v[206:209], v[124:127]
	v_mfma_f32_16x16x32_bf16 v[120:123], v[182:185], v[206:209], v[120:123]
	v_mfma_f32_16x16x32_bf16 v[116:119], v[174:177], v[214:217], v[116:119]
	v_mfma_f32_16x16x32_bf16 v[108:111], v[182:185], v[214:217], v[108:111]
	v_mfma_f32_16x16x32_bf16 v[100:103], v[174:177], v[222:225], v[100:103]
	v_mfma_f32_16x16x32_bf16 v[92:95], v[182:185], v[222:225], v[92:95]
	v_mfma_f32_16x16x32_bf16 v[84:87], v[174:177], v[234:237], v[84:87]
	v_mfma_f32_16x16x32_bf16 v[76:79], v[182:185], v[234:237], v[76:79]
	s_setprio 0
	s_setprio 1
	v_mfma_f32_16x16x32_bf16 v[112:115], v[186:189], v[202:205], v[112:115]
	v_mfma_f32_16x16x32_bf16 v[104:107], v[194:197], v[202:205], v[104:107]
	v_mfma_f32_16x16x32_bf16 v[96:99], v[186:189], v[210:213], v[96:99]
	v_mfma_f32_16x16x32_bf16 v[88:91], v[194:197], v[210:213], v[88:91]
	v_mfma_f32_16x16x32_bf16 v[80:83], v[186:189], v[218:221], v[80:83]
	v_mfma_f32_16x16x32_bf16 v[72:75], v[194:197], v[218:221], v[72:75]
	v_mfma_f32_16x16x32_bf16 v[68:71], v[186:189], v[230:233], v[68:71]
	v_mfma_f32_16x16x32_bf16 v[64:67], v[194:197], v[230:233], v[64:67]
	v_mfma_f32_16x16x32_bf16 v[112:115], v[190:193], v[206:209], v[112:115]
	v_mfma_f32_16x16x32_bf16 v[104:107], v[198:201], v[206:209], v[104:107]
	v_mfma_f32_16x16x32_bf16 v[96:99], v[190:193], v[214:217], v[96:99]
	v_mfma_f32_16x16x32_bf16 v[88:91], v[198:201], v[214:217], v[88:91]
	v_mfma_f32_16x16x32_bf16 v[80:83], v[190:193], v[222:225], v[80:83]
	v_mfma_f32_16x16x32_bf16 v[72:75], v[198:201], v[222:225], v[72:75]
	v_mfma_f32_16x16x32_bf16 v[68:71], v[190:193], v[234:237], v[68:71]
	v_mfma_f32_16x16x32_bf16 v[64:67], v[198:201], v[234:237], v[64:67]
	s_setprio 0
	s_barrier
	v_readfirstlane_b32 s24, v154
	v_lshl_add_u64 v[226:227], v[226:227], 0, s[6:7]
	s_mov_b32 m0, s24
	v_readfirstlane_b32 s24, v155
	s_add_u32 s22, s22, 0x40080
	ds_read_b128 v[202:205], v164 offset:49152
	ds_read_b128 v[206:209], v164 offset:50176
	ds_read_b128 v[210:213], v164 offset:51200
	ds_read_b128 v[214:217], v164 offset:52224
	ds_read_b128 v[218:221], v164 offset:53248
	ds_read_b128 v[222:225], v164 offset:54272
	ds_read_b128 v[230:233], v164 offset:55296
	ds_read_b128 v[234:237], v164 offset:56320
	global_load_lds_dwordx4 v[226:227], off
	v_lshl_add_u64 v[226:227], v[238:239], 0, s[6:7]
	s_mov_b32 m0, s24
	s_addc_u32 s23, s23, 0
	v_readfirstlane_b32 s24, v158
	global_load_lds_dwordx4 v[226:227], off
	v_lshl_add_u64 v[226:227], s[22:23], 0, v[130:131]
	s_mov_b32 m0, s24
	s_nop 0
	global_load_lds_dwordx4 v[226:227], off
	v_lshl_add_u64 v[226:227], s[22:23], 0, v[134:135]
	v_readfirstlane_b32 s22, v159
	s_mov_b32 m0, s22
	v_readfirstlane_b32 s22, v156
	global_load_lds_dwordx4 v[226:227], off
	v_lshl_add_u64 v[226:227], v[240:241], 0, s[6:7]
	s_mov_b32 m0, s22
	v_readfirstlane_b32 s22, v157
	global_load_lds_dwordx4 v[226:227], off
	v_lshl_add_u64 v[226:227], v[242:243], 0, s[6:7]
	s_mov_b32 m0, s22
	s_nop 0
	global_load_lds_dwordx4 v[226:227], off
	s_waitcnt vmcnt(8)
	s_waitcnt lgkmcnt(0)
	s_barrier
	s_setprio 1
	s_waitcnt lgkmcnt(0)
	v_mfma_f32_16x16x32_bf16 v[60:63], v[170:173], v[202:205], v[60:63]
	v_mfma_f32_16x16x32_bf16 v[56:59], v[178:181], v[202:205], v[56:59]
	v_mfma_f32_16x16x32_bf16 v[52:55], v[170:173], v[210:213], v[52:55]
	v_mfma_f32_16x16x32_bf16 v[44:47], v[178:181], v[210:213], v[44:47]
	v_mfma_f32_16x16x32_bf16 v[36:39], v[170:173], v[218:221], v[36:39]
	v_mfma_f32_16x16x32_bf16 v[28:31], v[178:181], v[218:221], v[28:31]
	v_mfma_f32_16x16x32_bf16 v[20:23], v[170:173], v[230:233], v[20:23]
	v_mfma_f32_16x16x32_bf16 v[12:15], v[178:181], v[230:233], v[12:15]
	v_mfma_f32_16x16x32_bf16 v[60:63], v[174:177], v[206:209], v[60:63]
	v_mfma_f32_16x16x32_bf16 v[56:59], v[182:185], v[206:209], v[56:59]
	v_mfma_f32_16x16x32_bf16 v[52:55], v[174:177], v[214:217], v[52:55]
	v_mfma_f32_16x16x32_bf16 v[44:47], v[182:185], v[214:217], v[44:47]
	v_mfma_f32_16x16x32_bf16 v[36:39], v[174:177], v[222:225], v[36:39]
	v_mfma_f32_16x16x32_bf16 v[28:31], v[182:185], v[222:225], v[28:31]
	v_mfma_f32_16x16x32_bf16 v[20:23], v[174:177], v[234:237], v[20:23]
	v_mfma_f32_16x16x32_bf16 v[12:15], v[182:185], v[234:237], v[12:15]
	s_setprio 0
	s_setprio 1
	v_mfma_f32_16x16x32_bf16 v[48:51], v[186:189], v[202:205], v[48:51]
	v_mfma_f32_16x16x32_bf16 v[40:43], v[194:197], v[202:205], v[40:43]
	v_mfma_f32_16x16x32_bf16 v[32:35], v[186:189], v[210:213], v[32:35]
	v_mfma_f32_16x16x32_bf16 v[24:27], v[194:197], v[210:213], v[24:27]
	v_mfma_f32_16x16x32_bf16 v[16:19], v[186:189], v[218:221], v[16:19]
	v_mfma_f32_16x16x32_bf16 v[8:11], v[194:197], v[218:221], v[8:11]
	v_mfma_f32_16x16x32_bf16 v[4:7], v[186:189], v[230:233], v[4:7]
	v_mfma_f32_16x16x32_bf16 v[0:3], v[194:197], v[230:233], v[0:3]
	v_mfma_f32_16x16x32_bf16 v[48:51], v[190:193], v[206:209], v[48:51]
	v_mfma_f32_16x16x32_bf16 v[40:43], v[198:201], v[206:209], v[40:43]
	v_mfma_f32_16x16x32_bf16 v[32:35], v[190:193], v[214:217], v[32:35]
	v_mfma_f32_16x16x32_bf16 v[24:27], v[198:201], v[214:217], v[24:27]
	v_mfma_f32_16x16x32_bf16 v[16:19], v[190:193], v[222:225], v[16:19]
	v_mfma_f32_16x16x32_bf16 v[8:11], v[198:201], v[222:225], v[8:11]
	v_mfma_f32_16x16x32_bf16 v[4:7], v[190:193], v[234:237], v[4:7]
	v_mfma_f32_16x16x32_bf16 v[0:3], v[198:201], v[234:237], v[0:3]
	s_setprio 0
	s_barrier
	s_add_i32 s41, s41, 2
	s_add_u32 s20, s20, 0x100
	s_addc_u32 s21, s21, 0
	s_add_u32 s39, s39, 0x100
	s_addc_u32 s40, s40, 0
.LBB0_118:
	ds_read_b128 v[170:173], v162
	ds_read_b128 v[174:177], v162 offset:1024
	ds_read_b128 v[178:181], v162 offset:2048
	ds_read_b128 v[182:185], v162 offset:3072
	ds_read_b128 v[186:189], v163
	ds_read_b128 v[190:193], v163 offset:1024
	ds_read_b128 v[194:197], v163 offset:2048
	ds_read_b128 v[198:201], v163 offset:3072
	s_add_u32 s22, s20, 0xfffc0080
	s_addc_u32 s23, s21, -1
	s_cmp_eq_u32 s41, 12
	s_cselect_b32 s25, s13, s23
	s_cselect_b32 s24, s37, s22
	s_cselect_b32 s23, s11, s40
	s_cselect_b32 s22, s38, s39
	v_readfirstlane_b32 s42, v165
	v_lshl_add_u64 v[226:227], s[20:21], 0, v[136:137]
	s_mov_b32 m0, s42
	v_readfirstlane_b32 s42, v166
	ds_read_b128 v[202:205], v164
	ds_read_b128 v[206:209], v164 offset:1024
	ds_read_b128 v[210:213], v164 offset:2048
	ds_read_b128 v[214:217], v164 offset:3072
	ds_read_b128 v[218:221], v164 offset:4096
	ds_read_b128 v[222:225], v164 offset:5120
	ds_read_b128 v[230:233], v164 offset:6144
	ds_read_b128 v[234:237], v164 offset:7168
	global_load_lds_dwordx4 v[226:227], off
	v_lshl_add_u64 v[226:227], s[20:21], 0, v[138:139]
	s_mov_b32 m0, s42
	s_nop 0
	global_load_lds_dwordx4 v[226:227], off
	s_waitcnt vmcnt(8)
	s_waitcnt lgkmcnt(0)
	s_barrier
	s_setprio 1
	s_waitcnt lgkmcnt(0)
	v_mfma_f32_16x16x32_bf16 v[124:127], v[170:173], v[202:205], v[124:127]
	v_mfma_f32_16x16x32_bf16 v[120:123], v[178:181], v[202:205], v[120:123]
	v_mfma_f32_16x16x32_bf16 v[116:119], v[170:173], v[210:213], v[116:119]
	v_mfma_f32_16x16x32_bf16 v[108:111], v[178:181], v[210:213], v[108:111]
	v_mfma_f32_16x16x32_bf16 v[100:103], v[170:173], v[218:221], v[100:103]
	v_mfma_f32_16x16x32_bf16 v[92:95], v[178:181], v[218:221], v[92:95]
	v_mfma_f32_16x16x32_bf16 v[84:87], v[170:173], v[230:233], v[84:87]
	v_mfma_f32_16x16x32_bf16 v[76:79], v[178:181], v[230:233], v[76:79]
	v_mfma_f32_16x16x32_bf16 v[124:127], v[174:177], v[206:209], v[124:127]
	v_mfma_f32_16x16x32_bf16 v[120:123], v[182:185], v[206:209], v[120:123]
	v_mfma_f32_16x16x32_bf16 v[116:119], v[174:177], v[214:217], v[116:119]
	v_mfma_f32_16x16x32_bf16 v[108:111], v[182:185], v[214:217], v[108:111]
	v_mfma_f32_16x16x32_bf16 v[100:103], v[174:177], v[222:225], v[100:103]
	v_mfma_f32_16x16x32_bf16 v[92:95], v[182:185], v[222:225], v[92:95]
	v_mfma_f32_16x16x32_bf16 v[84:87], v[174:177], v[234:237], v[84:87]
	v_mfma_f32_16x16x32_bf16 v[76:79], v[182:185], v[234:237], v[76:79]
	s_setprio 0
	s_setprio 1
	v_mfma_f32_16x16x32_bf16 v[112:115], v[186:189], v[202:205], v[112:115]
	v_mfma_f32_16x16x32_bf16 v[104:107], v[194:197], v[202:205], v[104:107]
	v_mfma_f32_16x16x32_bf16 v[96:99], v[186:189], v[210:213], v[96:99]
	v_mfma_f32_16x16x32_bf16 v[88:91], v[194:197], v[210:213], v[88:91]
	v_mfma_f32_16x16x32_bf16 v[80:83], v[186:189], v[218:221], v[80:83]
	v_mfma_f32_16x16x32_bf16 v[72:75], v[194:197], v[218:221], v[72:75]
	v_mfma_f32_16x16x32_bf16 v[68:71], v[186:189], v[230:233], v[68:71]
	v_mfma_f32_16x16x32_bf16 v[64:67], v[194:197], v[230:233], v[64:67]
	v_mfma_f32_16x16x32_bf16 v[112:115], v[190:193], v[206:209], v[112:115]
	v_mfma_f32_16x16x32_bf16 v[104:107], v[198:201], v[206:209], v[104:107]
	v_mfma_f32_16x16x32_bf16 v[96:99], v[190:193], v[214:217], v[96:99]
	v_mfma_f32_16x16x32_bf16 v[88:91], v[198:201], v[214:217], v[88:91]
	v_mfma_f32_16x16x32_bf16 v[80:83], v[190:193], v[222:225], v[80:83]
	v_mfma_f32_16x16x32_bf16 v[72:75], v[198:201], v[222:225], v[72:75]
	v_mfma_f32_16x16x32_bf16 v[68:71], v[190:193], v[234:237], v[68:71]
	v_mfma_f32_16x16x32_bf16 v[64:67], v[198:201], v[234:237], v[64:67]
	s_setprio 0
	s_barrier
	v_readfirstlane_b32 s42, v146
	v_lshl_add_u64 v[226:227], s[22:23], 0, v[130:131]
	s_mov_b32 m0, s42
	v_readfirstlane_b32 s42, v147
	ds_read_b128 v[202:205], v164 offset:16384
	ds_read_b128 v[206:209], v164 offset:17408
	ds_read_b128 v[210:213], v164 offset:18432
	ds_read_b128 v[214:217], v164 offset:19456
	ds_read_b128 v[218:221], v164 offset:20480
	ds_read_b128 v[222:225], v164 offset:21504
	ds_read_b128 v[230:233], v164 offset:22528
	ds_read_b128 v[234:237], v164 offset:23552
	global_load_lds_dwordx4 v[226:227], off
	s_mov_b32 m0, s42
	s_add_u32 s42, s22, 0x40000
	v_lshl_add_u64 v[238:239], s[22:23], 0, v[134:135]
	s_addc_u32 s43, s23, 0
	v_readfirstlane_b32 s44, v148
	global_load_lds_dwordx4 v[238:239], off
	v_lshl_add_u64 v[240:241], s[42:43], 0, v[130:131]
	s_mov_b32 m0, s44
	v_lshl_add_u64 v[242:243], s[24:25], 0, v[132:133]
	global_load_lds_dwordx4 v[240:241], off
	v_lshl_add_u64 v[240:241], s[42:43], 0, v[134:135]
	v_readfirstlane_b32 s42, v149
	s_mov_b32 m0, s42
	v_readfirstlane_b32 s42, v150
	global_load_lds_dwordx4 v[240:241], off
	v_lshl_add_u64 v[240:241], s[24:25], 0, v[128:129]
	s_mov_b32 m0, s42
	v_readfirstlane_b32 s42, v151
	global_load_lds_dwordx4 v[240:241], off
	s_mov_b32 m0, s42
	s_nop 0
	global_load_lds_dwordx4 v[242:243], off
	s_waitcnt vmcnt(8)
	s_waitcnt lgkmcnt(0)
	s_barrier
	s_setprio 1
	s_waitcnt lgkmcnt(0)
	v_mfma_f32_16x16x32_bf16 v[60:63], v[170:173], v[202:205], v[60:63]
	v_mfma_f32_16x16x32_bf16 v[56:59], v[178:181], v[202:205], v[56:59]
	v_mfma_f32_16x16x32_bf16 v[52:55], v[170:173], v[210:213], v[52:55]
	v_mfma_f32_16x16x32_bf16 v[44:47], v[178:181], v[210:213], v[44:47]
	v_mfma_f32_16x16x32_bf16 v[36:39], v[170:173], v[218:221], v[36:39]
	v_mfma_f32_16x16x32_bf16 v[28:31], v[178:181], v[218:221], v[28:31]
	v_mfma_f32_16x16x32_bf16 v[20:23], v[170:173], v[230:233], v[20:23]
	v_mfma_f32_16x16x32_bf16 v[12:15], v[178:181], v[230:233], v[12:15]
	v_mfma_f32_16x16x32_bf16 v[60:63], v[174:177], v[206:209], v[60:63]
	v_mfma_f32_16x16x32_bf16 v[56:59], v[182:185], v[206:209], v[56:59]
	v_mfma_f32_16x16x32_bf16 v[52:55], v[174:177], v[214:217], v[52:55]
	v_mfma_f32_16x16x32_bf16 v[44:47], v[182:185], v[214:217], v[44:47]
	v_mfma_f32_16x16x32_bf16 v[36:39], v[174:177], v[222:225], v[36:39]
	v_mfma_f32_16x16x32_bf16 v[28:31], v[182:185], v[222:225], v[28:31]
	v_mfma_f32_16x16x32_bf16 v[20:23], v[174:177], v[234:237], v[20:23]
	v_mfma_f32_16x16x32_bf16 v[12:15], v[182:185], v[234:237], v[12:15]
	s_setprio 0
	s_setprio 1
	v_mfma_f32_16x16x32_bf16 v[48:51], v[186:189], v[202:205], v[48:51]
	v_mfma_f32_16x16x32_bf16 v[40:43], v[194:197], v[202:205], v[40:43]
	v_mfma_f32_16x16x32_bf16 v[32:35], v[186:189], v[210:213], v[32:35]
	v_mfma_f32_16x16x32_bf16 v[24:27], v[194:197], v[210:213], v[24:27]
	v_mfma_f32_16x16x32_bf16 v[16:19], v[186:189], v[218:221], v[16:19]
	v_mfma_f32_16x16x32_bf16 v[8:11], v[194:197], v[218:221], v[8:11]
	v_mfma_f32_16x16x32_bf16 v[4:7], v[186:189], v[230:233], v[4:7]
	v_mfma_f32_16x16x32_bf16 v[0:3], v[194:197], v[230:233], v[0:3]
	v_mfma_f32_16x16x32_bf16 v[48:51], v[190:193], v[206:209], v[48:51]
	v_mfma_f32_16x16x32_bf16 v[40:43], v[198:201], v[206:209], v[40:43]
	v_mfma_f32_16x16x32_bf16 v[32:35], v[190:193], v[214:217], v[32:35]
	v_mfma_f32_16x16x32_bf16 v[24:27], v[198:201], v[214:217], v[24:27]
	v_mfma_f32_16x16x32_bf16 v[16:19], v[190:193], v[222:225], v[16:19]
	v_mfma_f32_16x16x32_bf16 v[8:11], v[198:201], v[222:225], v[8:11]
	v_mfma_f32_16x16x32_bf16 v[4:7], v[190:193], v[234:237], v[4:7]
	v_mfma_f32_16x16x32_bf16 v[0:3], v[198:201], v[234:237], v[0:3]
	s_setprio 0
	s_barrier
	ds_read_b128 v[170:173], v167
	ds_read_b128 v[174:177], v167 offset:1024
	ds_read_b128 v[178:181], v167 offset:2048
	ds_read_b128 v[182:185], v167 offset:3072
	ds_read_b128 v[186:189], v168
	ds_read_b128 v[190:193], v168 offset:1024
	ds_read_b128 v[194:197], v168 offset:2048
	ds_read_b128 v[198:201], v168 offset:3072
	s_add_u32 s24, s24, 0x40000
	s_addc_u32 s25, s25, 0
	v_readfirstlane_b32 s42, v152
	v_lshl_add_u64 v[244:245], s[24:25], 0, v[128:129]
	s_mov_b32 m0, s42
	ds_read_b128 v[202:205], v164 offset:32768
	ds_read_b128 v[206:209], v164 offset:33792
	ds_read_b128 v[210:213], v164 offset:34816
	ds_read_b128 v[214:217], v164 offset:35840
	ds_read_b128 v[218:221], v164 offset:36864
	ds_read_b128 v[222:225], v164 offset:37888
	ds_read_b128 v[230:233], v164 offset:38912
	ds_read_b128 v[234:237], v164 offset:39936
	global_load_lds_dwordx4 v[244:245], off
	v_lshl_add_u64 v[244:245], s[24:25], 0, v[132:133]
	v_readfirstlane_b32 s24, v153
	s_mov_b32 m0, s24
	s_nop 0
	global_load_lds_dwordx4 v[244:245], off
	s_waitcnt vmcnt(8)
	s_waitcnt lgkmcnt(0)
	s_barrier
	s_setprio 1
	s_waitcnt lgkmcnt(0)
	v_mfma_f32_16x16x32_bf16 v[124:127], v[170:173], v[202:205], v[124:127]
	v_mfma_f32_16x16x32_bf16 v[120:123], v[178:181], v[202:205], v[120:123]
	v_mfma_f32_16x16x32_bf16 v[116:119], v[170:173], v[210:213], v[116:119]
	v_mfma_f32_16x16x32_bf16 v[108:111], v[178:181], v[210:213], v[108:111]
	v_mfma_f32_16x16x32_bf16 v[100:103], v[170:173], v[218:221], v[100:103]
	v_mfma_f32_16x16x32_bf16 v[92:95], v[178:181], v[218:221], v[92:95]
	v_mfma_f32_16x16x32_bf16 v[84:87], v[170:173], v[230:233], v[84:87]
	v_mfma_f32_16x16x32_bf16 v[76:79], v[178:181], v[230:233], v[76:79]
	v_mfma_f32_16x16x32_bf16 v[124:127], v[174:177], v[206:209], v[124:127]
	v_mfma_f32_16x16x32_bf16 v[120:123], v[182:185], v[206:209], v[120:123]
	v_mfma_f32_16x16x32_bf16 v[116:119], v[174:177], v[214:217], v[116:119]
	v_mfma_f32_16x16x32_bf16 v[108:111], v[182:185], v[214:217], v[108:111]
	v_mfma_f32_16x16x32_bf16 v[100:103], v[174:177], v[222:225], v[100:103]
	v_mfma_f32_16x16x32_bf16 v[92:95], v[182:185], v[222:225], v[92:95]
	v_mfma_f32_16x16x32_bf16 v[84:87], v[174:177], v[234:237], v[84:87]
	v_mfma_f32_16x16x32_bf16 v[76:79], v[182:185], v[234:237], v[76:79]
	s_setprio 0
	s_setprio 1
	v_mfma_f32_16x16x32_bf16 v[112:115], v[186:189], v[202:205], v[112:115]
	v_mfma_f32_16x16x32_bf16 v[104:107], v[194:197], v[202:205], v[104:107]
	v_mfma_f32_16x16x32_bf16 v[96:99], v[186:189], v[210:213], v[96:99]
	v_mfma_f32_16x16x32_bf16 v[88:91], v[194:197], v[210:213], v[88:91]
	v_mfma_f32_16x16x32_bf16 v[80:83], v[186:189], v[218:221], v[80:83]
	v_mfma_f32_16x16x32_bf16 v[72:75], v[194:197], v[218:221], v[72:75]
	v_mfma_f32_16x16x32_bf16 v[68:71], v[186:189], v[230:233], v[68:71]
	v_mfma_f32_16x16x32_bf16 v[64:67], v[194:197], v[230:233], v[64:67]
	v_mfma_f32_16x16x32_bf16 v[112:115], v[190:193], v[206:209], v[112:115]
	v_mfma_f32_16x16x32_bf16 v[104:107], v[198:201], v[206:209], v[104:107]
	v_mfma_f32_16x16x32_bf16 v[96:99], v[190:193], v[214:217], v[96:99]
	v_mfma_f32_16x16x32_bf16 v[88:91], v[198:201], v[214:217], v[88:91]
	v_mfma_f32_16x16x32_bf16 v[80:83], v[190:193], v[222:225], v[80:83]
	v_mfma_f32_16x16x32_bf16 v[72:75], v[198:201], v[222:225], v[72:75]
	v_mfma_f32_16x16x32_bf16 v[68:71], v[190:193], v[234:237], v[68:71]
	v_mfma_f32_16x16x32_bf16 v[64:67], v[198:201], v[234:237], v[64:67]
	s_setprio 0
	s_barrier
	v_readfirstlane_b32 s24, v154
	v_lshl_add_u64 v[226:227], v[226:227], 0, s[6:7]
	s_mov_b32 m0, s24
	v_readfirstlane_b32 s24, v155
	s_add_u32 s22, s22, 0x40080
	ds_read_b128 v[202:205], v164 offset:49152
	ds_read_b128 v[206:209], v164 offset:50176
	ds_read_b128 v[210:213], v164 offset:51200
	ds_read_b128 v[214:217], v164 offset:52224
	ds_read_b128 v[218:221], v164 offset:53248
	ds_read_b128 v[222:225], v164 offset:54272
	ds_read_b128 v[230:233], v164 offset:55296
	ds_read_b128 v[234:237], v164 offset:56320
	global_load_lds_dwordx4 v[226:227], off
	v_lshl_add_u64 v[226:227], v[238:239], 0, s[6:7]
	s_mov_b32 m0, s24
	s_addc_u32 s23, s23, 0
	v_readfirstlane_b32 s24, v158
	global_load_lds_dwordx4 v[226:227], off
	v_lshl_add_u64 v[226:227], s[22:23], 0, v[130:131]
	s_mov_b32 m0, s24
	s_nop 0
	global_load_lds_dwordx4 v[226:227], off
	v_lshl_add_u64 v[226:227], s[22:23], 0, v[134:135]
	v_readfirstlane_b32 s22, v159
	s_mov_b32 m0, s22
	v_readfirstlane_b32 s22, v156
	global_load_lds_dwordx4 v[226:227], off
	v_lshl_add_u64 v[226:227], v[240:241], 0, s[6:7]
	s_mov_b32 m0, s22
	v_readfirstlane_b32 s22, v157
	global_load_lds_dwordx4 v[226:227], off
	v_lshl_add_u64 v[226:227], v[242:243], 0, s[6:7]
	s_mov_b32 m0, s22
	s_nop 0
	global_load_lds_dwordx4 v[226:227], off
	s_waitcnt vmcnt(8)
	s_waitcnt lgkmcnt(0)
	s_barrier
	s_setprio 1
	s_waitcnt lgkmcnt(0)
	v_mfma_f32_16x16x32_bf16 v[60:63], v[170:173], v[202:205], v[60:63]
	v_mfma_f32_16x16x32_bf16 v[56:59], v[178:181], v[202:205], v[56:59]
	v_mfma_f32_16x16x32_bf16 v[52:55], v[170:173], v[210:213], v[52:55]
	v_mfma_f32_16x16x32_bf16 v[44:47], v[178:181], v[210:213], v[44:47]
	v_mfma_f32_16x16x32_bf16 v[36:39], v[170:173], v[218:221], v[36:39]
	v_mfma_f32_16x16x32_bf16 v[28:31], v[178:181], v[218:221], v[28:31]
	v_mfma_f32_16x16x32_bf16 v[20:23], v[170:173], v[230:233], v[20:23]
	v_mfma_f32_16x16x32_bf16 v[12:15], v[178:181], v[230:233], v[12:15]
	v_mfma_f32_16x16x32_bf16 v[60:63], v[174:177], v[206:209], v[60:63]
	v_mfma_f32_16x16x32_bf16 v[56:59], v[182:185], v[206:209], v[56:59]
	v_mfma_f32_16x16x32_bf16 v[52:55], v[174:177], v[214:217], v[52:55]
	v_mfma_f32_16x16x32_bf16 v[44:47], v[182:185], v[214:217], v[44:47]
	v_mfma_f32_16x16x32_bf16 v[36:39], v[174:177], v[222:225], v[36:39]
	v_mfma_f32_16x16x32_bf16 v[28:31], v[182:185], v[222:225], v[28:31]
	v_mfma_f32_16x16x32_bf16 v[20:23], v[174:177], v[234:237], v[20:23]
	v_mfma_f32_16x16x32_bf16 v[12:15], v[182:185], v[234:237], v[12:15]
	s_setprio 0
	s_setprio 1
	v_mfma_f32_16x16x32_bf16 v[48:51], v[186:189], v[202:205], v[48:51]
	v_mfma_f32_16x16x32_bf16 v[40:43], v[194:197], v[202:205], v[40:43]
	v_mfma_f32_16x16x32_bf16 v[32:35], v[186:189], v[210:213], v[32:35]
	v_mfma_f32_16x16x32_bf16 v[24:27], v[194:197], v[210:213], v[24:27]
	v_mfma_f32_16x16x32_bf16 v[16:19], v[186:189], v[218:221], v[16:19]
	v_mfma_f32_16x16x32_bf16 v[8:11], v[194:197], v[218:221], v[8:11]
	v_mfma_f32_16x16x32_bf16 v[4:7], v[186:189], v[230:233], v[4:7]
	v_mfma_f32_16x16x32_bf16 v[0:3], v[194:197], v[230:233], v[0:3]
	v_mfma_f32_16x16x32_bf16 v[48:51], v[190:193], v[206:209], v[48:51]
	v_mfma_f32_16x16x32_bf16 v[40:43], v[198:201], v[206:209], v[40:43]
	v_mfma_f32_16x16x32_bf16 v[32:35], v[190:193], v[214:217], v[32:35]
	v_mfma_f32_16x16x32_bf16 v[24:27], v[198:201], v[214:217], v[24:27]
	v_mfma_f32_16x16x32_bf16 v[16:19], v[190:193], v[222:225], v[16:19]
	v_mfma_f32_16x16x32_bf16 v[8:11], v[198:201], v[222:225], v[8:11]
	v_mfma_f32_16x16x32_bf16 v[4:7], v[190:193], v[234:237], v[4:7]
	v_mfma_f32_16x16x32_bf16 v[0:3], v[198:201], v[234:237], v[0:3]
	s_setprio 0
	s_barrier
	s_add_i32 s41, s41, 2
	s_add_u32 s20, s20, 0x100
	s_addc_u32 s21, s21, 0
	s_add_u32 s39, s39, 0x100
	s_addc_u32 s40, s40, 0
	s_cmp_gt_u32 s41, 13
	s_cbranch_scc0 .LBB0_118
	s_add_u32 s100, s37, 0x40080
	s_addc_u32 s101, s13, 0
	v_readfirstlane_b32 s42, v165
	v_lshl_add_u64 v[226:227], s[100:101], 0, v[136:137]
	s_mov_b32 m0, s42
	v_readfirstlane_b32 s42, v166
	global_load_lds_dwordx4 v[226:227], off
	v_lshl_add_u64 v[226:227], s[100:101], 0, v[138:139]
	s_mov_b32 m0, s42
	s_nop 0
	global_load_lds_dwordx4 v[226:227], off
	s_and_b64 vcc, exec, s[8:9]
	s_cbranch_vccz .LBB0_121
	s_barrier

.LBB0_1300:
	s_ashr_i32 s15, s14, 31
	s_lshl_b64 s[16:17], s[14:15], 19
	s_add_u32 s16, s31, s16
	s_addc_u32 s17, s33, s17
	s_and_b64 s[18:19], s[2:3], exec
	s_cselect_b32 s15, s17, s23
	s_cselect_b32 s38, s16, s22
	s_ashr_i32 s13, s12, 31
	s_lshl_b64 s[18:19], s[12:13], 19
	s_add_u32 s18, s29, s18
	s_addc_u32 s19, s30, s19
	s_and_b64 s[26:27], s[2:3], exec
	s_cselect_b32 s13, s19, s25
	s_cselect_b32 s39, s18, s24
	s_add_u32 s22, s22, 0x40080
	s_addc_u32 s23, s23, 0
	s_add_u32 s40, s24, 0x100
	s_addc_u32 s41, s25, 0
	s_mov_b32 s42, -2
	ds_read_b128 v[170:173], v163
	ds_read_b128 v[174:177], v163 offset:1024
	ds_read_b128 v[178:181], v163 offset:2048
	ds_read_b128 v[182:185], v163 offset:3072
	ds_read_b128 v[186:189], v164
	ds_read_b128 v[190:193], v164 offset:1024
	ds_read_b128 v[194:197], v164 offset:2048
	ds_read_b128 v[198:201], v164 offset:3072
	s_add_u32 s24, s22, 0xfffc0080
	s_addc_u32 s25, s23, -1
	s_cmp_eq_u32 s42, 12
	s_cselect_b32 s27, s15, s25
	s_cselect_b32 s26, s38, s24
	s_cselect_b32 s25, s13, s41
	s_cselect_b32 s24, s39, s40
	v_readfirstlane_b32 s43, v166
	v_lshl_add_u64 v[144:145], s[22:23], 0, v[136:137]
	s_mov_b32 m0, s43
	v_readfirstlane_b32 s43, v167
	ds_read_b128 v[202:205], v165
	ds_read_b128 v[206:209], v165 offset:1024
	ds_read_b128 v[210:213], v165 offset:2048
	ds_read_b128 v[214:217], v165 offset:3072
	ds_read_b128 v[218:221], v165 offset:4096
	ds_read_b128 v[222:225], v165 offset:5120
	ds_read_b128 v[230:233], v165 offset:6144
	ds_read_b128 v[234:237], v165 offset:7168
	s_cmp_lg_u32 s21, 1
	s_cbranch_scc1 .Lpeel_st_g3l0
	global_load_lds_dwordx4 v[144:145], off
	v_lshl_add_u64 v[144:145], s[22:23], 0, v[138:139]
	s_mov_b32 m0, s43
	s_nop 0
	global_load_lds_dwordx4 v[144:145], off
.Lpeel_st_g3l0:
	s_waitcnt vmcnt(16)
	s_waitcnt lgkmcnt(0)
	s_barrier
	s_setprio 1
	s_waitcnt lgkmcnt(0)
	v_mfma_f32_16x16x32_bf16 v[124:127], v[170:173], v[202:205], 0
	v_mfma_f32_16x16x32_bf16 v[120:123], v[178:181], v[202:205], 0
	v_mfma_f32_16x16x32_bf16 v[108:111], v[170:173], v[210:213], 0
	v_mfma_f32_16x16x32_bf16 v[104:107], v[178:181], v[210:213], 0
	v_mfma_f32_16x16x32_bf16 v[92:95], v[170:173], v[218:221], 0
	v_mfma_f32_16x16x32_bf16 v[88:91], v[178:181], v[218:221], 0
	v_mfma_f32_16x16x32_bf16 v[76:79], v[170:173], v[230:233], 0
	v_mfma_f32_16x16x32_bf16 v[72:75], v[178:181], v[230:233], 0
	v_mfma_f32_16x16x32_bf16 v[124:127], v[174:177], v[206:209], v[124:127]
	v_mfma_f32_16x16x32_bf16 v[120:123], v[182:185], v[206:209], v[120:123]
	v_mfma_f32_16x16x32_bf16 v[108:111], v[174:177], v[214:217], v[108:111]
	v_mfma_f32_16x16x32_bf16 v[104:107], v[182:185], v[214:217], v[104:107]
	v_mfma_f32_16x16x32_bf16 v[92:95], v[174:177], v[222:225], v[92:95]
	v_mfma_f32_16x16x32_bf16 v[88:91], v[182:185], v[222:225], v[88:91]
	v_mfma_f32_16x16x32_bf16 v[76:79], v[174:177], v[234:237], v[76:79]
	v_mfma_f32_16x16x32_bf16 v[72:75], v[182:185], v[234:237], v[72:75]
	s_setprio 0
	s_setprio 1
	v_mfma_f32_16x16x32_bf16 v[116:119], v[186:189], v[202:205], 0
	v_mfma_f32_16x16x32_bf16 v[112:115], v[194:197], v[202:205], 0
	v_mfma_f32_16x16x32_bf16 v[100:103], v[186:189], v[210:213], 0
	v_mfma_f32_16x16x32_bf16 v[96:99], v[194:197], v[210:213], 0
	v_mfma_f32_16x16x32_bf16 v[84:87], v[186:189], v[218:221], 0
	v_mfma_f32_16x16x32_bf16 v[80:83], v[194:197], v[218:221], 0
	v_mfma_f32_16x16x32_bf16 v[68:71], v[186:189], v[230:233], 0
	v_mfma_f32_16x16x32_bf16 v[64:67], v[194:197], v[230:233], 0
	v_mfma_f32_16x16x32_bf16 v[116:119], v[190:193], v[206:209], v[116:119]
	v_mfma_f32_16x16x32_bf16 v[112:115], v[198:201], v[206:209], v[112:115]
	v_mfma_f32_16x16x32_bf16 v[100:103], v[190:193], v[214:217], v[100:103]
	v_mfma_f32_16x16x32_bf16 v[96:99], v[198:201], v[214:217], v[96:99]
	v_mfma_f32_16x16x32_bf16 v[84:87], v[190:193], v[222:225], v[84:87]
	v_mfma_f32_16x16x32_bf16 v[80:83], v[198:201], v[222:225], v[80:83]
	v_mfma_f32_16x16x32_bf16 v[68:71], v[190:193], v[234:237], v[68:71]
	v_mfma_f32_16x16x32_bf16 v[64:67], v[198:201], v[234:237], v[64:67]
	s_setprio 0
	s_barrier
	v_readfirstlane_b32 s43, v147
	v_lshl_add_u64 v[144:145], s[24:25], 0, v[130:131]
	s_mov_b32 m0, s43
	v_readfirstlane_b32 s43, v148
	s_add_u32 s44, s24, 0x40000
	ds_read_b128 v[202:205], v165 offset:16384
	ds_read_b128 v[206:209], v165 offset:17408
	ds_read_b128 v[210:213], v165 offset:18432
	ds_read_b128 v[214:217], v165 offset:19456
	ds_read_b128 v[218:221], v165 offset:20480
	ds_read_b128 v[222:225], v165 offset:21504
	ds_read_b128 v[230:233], v165 offset:22528
	ds_read_b128 v[234:237], v165 offset:23552
	global_load_lds_dwordx4 v[144:145], off
	v_lshl_add_u64 v[226:227], s[24:25], 0, v[134:135]
	s_mov_b32 m0, s43
	s_addc_u32 s45, s25, 0
	v_readfirstlane_b32 s43, v149
	global_load_lds_dwordx4 v[226:227], off
	v_lshl_add_u64 v[238:239], s[44:45], 0, v[130:131]
	s_mov_b32 m0, s43
	v_readfirstlane_b32 s43, v150
	global_load_lds_dwordx4 v[238:239], off
	v_lshl_add_u64 v[238:239], s[44:45], 0, v[134:135]
	s_mov_b32 m0, s43
	v_readfirstlane_b32 s43, v151
	global_load_lds_dwordx4 v[238:239], off
	v_lshl_add_u64 v[238:239], s[26:27], 0, v[128:129]
	s_mov_b32 m0, s43
	v_readfirstlane_b32 s43, v152
	global_load_lds_dwordx4 v[238:239], off
	v_lshl_add_u64 v[240:241], s[26:27], 0, v[132:133]
	s_mov_b32 m0, s43
	s_nop 0
	global_load_lds_dwordx4 v[240:241], off
	s_waitcnt vmcnt(16)
	s_cmp_lg_u32 s21, 1
	s_cbranch_scc1 .Lpeel_w2_g3l0
	s_waitcnt vmcnt(8)
.Lpeel_w2_g3l0:
	s_waitcnt lgkmcnt(0)
	s_barrier
	s_setprio 1
	s_waitcnt lgkmcnt(0)
	v_mfma_f32_16x16x32_bf16 v[60:63], v[170:173], v[202:205], 0
	v_mfma_f32_16x16x32_bf16 v[56:59], v[178:181], v[202:205], 0
	v_mfma_f32_16x16x32_bf16 v[44:47], v[170:173], v[210:213], 0
	v_mfma_f32_16x16x32_bf16 v[40:43], v[178:181], v[210:213], 0
	v_mfma_f32_16x16x32_bf16 v[28:31], v[170:173], v[218:221], 0
	v_mfma_f32_16x16x32_bf16 v[24:27], v[178:181], v[218:221], 0
	v_mfma_f32_16x16x32_bf16 v[12:15], v[170:173], v[230:233], 0
	v_mfma_f32_16x16x32_bf16 v[8:11], v[178:181], v[230:233], 0
	v_mfma_f32_16x16x32_bf16 v[60:63], v[174:177], v[206:209], v[60:63]
	v_mfma_f32_16x16x32_bf16 v[56:59], v[182:185], v[206:209], v[56:59]
	v_mfma_f32_16x16x32_bf16 v[44:47], v[174:177], v[214:217], v[44:47]
	v_mfma_f32_16x16x32_bf16 v[40:43], v[182:185], v[214:217], v[40:43]
	v_mfma_f32_16x16x32_bf16 v[28:31], v[174:177], v[222:225], v[28:31]
	v_mfma_f32_16x16x32_bf16 v[24:27], v[182:185], v[222:225], v[24:27]
	v_mfma_f32_16x16x32_bf16 v[12:15], v[174:177], v[234:237], v[12:15]
	v_mfma_f32_16x16x32_bf16 v[8:11], v[182:185], v[234:237], v[8:11]
	s_setprio 0
	s_setprio 1
	v_mfma_f32_16x16x32_bf16 v[52:55], v[186:189], v[202:205], 0
	v_mfma_f32_16x16x32_bf16 v[48:51], v[194:197], v[202:205], 0
	v_mfma_f32_16x16x32_bf16 v[36:39], v[186:189], v[210:213], 0
	v_mfma_f32_16x16x32_bf16 v[32:35], v[194:197], v[210:213], 0
	v_mfma_f32_16x16x32_bf16 v[20:23], v[186:189], v[218:221], 0
	v_mfma_f32_16x16x32_bf16 v[16:19], v[194:197], v[218:221], 0
	v_mfma_f32_16x16x32_bf16 v[4:7], v[186:189], v[230:233], 0
	v_mfma_f32_16x16x32_bf16 v[0:3], v[194:197], v[230:233], 0
	v_mfma_f32_16x16x32_bf16 v[52:55], v[190:193], v[206:209], v[52:55]
	v_mfma_f32_16x16x32_bf16 v[48:51], v[198:201], v[206:209], v[48:51]
	v_mfma_f32_16x16x32_bf16 v[36:39], v[190:193], v[214:217], v[36:39]
	v_mfma_f32_16x16x32_bf16 v[32:35], v[198:201], v[214:217], v[32:35]
	v_mfma_f32_16x16x32_bf16 v[20:23], v[190:193], v[222:225], v[20:23]
	v_mfma_f32_16x16x32_bf16 v[16:19], v[198:201], v[222:225], v[16:19]
	v_mfma_f32_16x16x32_bf16 v[4:7], v[190:193], v[234:237], v[4:7]
	v_mfma_f32_16x16x32_bf16 v[0:3], v[198:201], v[234:237], v[0:3]
	s_setprio 0
	s_barrier
	ds_read_b128 v[170:173], v168
	ds_read_b128 v[174:177], v168 offset:1024
	ds_read_b128 v[178:181], v168 offset:2048
	ds_read_b128 v[182:185], v168 offset:3072
	ds_read_b128 v[186:189], v169
	ds_read_b128 v[190:193], v169 offset:1024
	ds_read_b128 v[194:197], v169 offset:2048
	ds_read_b128 v[198:201], v169 offset:3072
	s_add_u32 s26, s26, 0x40000
	s_addc_u32 s27, s27, 0
	v_readfirstlane_b32 s43, v153
	v_lshl_add_u64 v[242:243], s[26:27], 0, v[128:129]
	s_mov_b32 m0, s43
	ds_read_b128 v[202:205], v165 offset:32768
	ds_read_b128 v[206:209], v165 offset:33792
	ds_read_b128 v[210:213], v165 offset:34816
	ds_read_b128 v[214:217], v165 offset:35840
	ds_read_b128 v[218:221], v165 offset:36864
	ds_read_b128 v[222:225], v165 offset:37888
	ds_read_b128 v[230:233], v165 offset:38912
	ds_read_b128 v[234:237], v165 offset:39936
	global_load_lds_dwordx4 v[242:243], off
	v_lshl_add_u64 v[242:243], s[26:27], 0, v[132:133]
	v_readfirstlane_b32 s26, v154
	s_mov_b32 m0, s26
	s_nop 0
	global_load_lds_dwordx4 v[242:243], off
	s_waitcnt vmcnt(16)
	s_cmp_lg_u32 s21, 1
	s_cbranch_scc1 .Lpeel_w3_g3l0
	s_waitcnt vmcnt(8)
.Lpeel_w3_g3l0:
	s_waitcnt lgkmcnt(0)
	s_barrier
	s_setprio 1
	s_waitcnt lgkmcnt(0)
	v_mfma_f32_16x16x32_bf16 v[124:127], v[170:173], v[202:205], v[124:127]
	v_mfma_f32_16x16x32_bf16 v[120:123], v[178:181], v[202:205], v[120:123]
	v_mfma_f32_16x16x32_bf16 v[108:111], v[170:173], v[210:213], v[108:111]
	v_mfma_f32_16x16x32_bf16 v[104:107], v[178:181], v[210:213], v[104:107]
	v_mfma_f32_16x16x32_bf16 v[92:95], v[170:173], v[218:221], v[92:95]
	v_mfma_f32_16x16x32_bf16 v[88:91], v[178:181], v[218:221], v[88:91]
	v_mfma_f32_16x16x32_bf16 v[76:79], v[170:173], v[230:233], v[76:79]
	v_mfma_f32_16x16x32_bf16 v[72:75], v[178:181], v[230:233], v[72:75]
	v_mfma_f32_16x16x32_bf16 v[124:127], v[174:177], v[206:209], v[124:127]
	v_mfma_f32_16x16x32_bf16 v[120:123], v[182:185], v[206:209], v[120:123]
	v_mfma_f32_16x16x32_bf16 v[108:111], v[174:177], v[214:217], v[108:111]
	v_mfma_f32_16x16x32_bf16 v[104:107], v[182:185], v[214:217], v[104:107]
	v_mfma_f32_16x16x32_bf16 v[92:95], v[174:177], v[222:225], v[92:95]
	v_mfma_f32_16x16x32_bf16 v[88:91], v[182:185], v[222:225], v[88:91]
	v_mfma_f32_16x16x32_bf16 v[76:79], v[174:177], v[234:237], v[76:79]
	v_mfma_f32_16x16x32_bf16 v[72:75], v[182:185], v[234:237], v[72:75]
	s_setprio 0
	s_setprio 1
	v_mfma_f32_16x16x32_bf16 v[116:119], v[186:189], v[202:205], v[116:119]
	v_mfma_f32_16x16x32_bf16 v[112:115], v[194:197], v[202:205], v[112:115]
	v_mfma_f32_16x16x32_bf16 v[100:103], v[186:189], v[210:213], v[100:103]
	v_mfma_f32_16x16x32_bf16 v[96:99], v[194:197], v[210:213], v[96:99]
	v_mfma_f32_16x16x32_bf16 v[84:87], v[186:189], v[218:221], v[84:87]
	v_mfma_f32_16x16x32_bf16 v[80:83], v[194:197], v[218:221], v[80:83]
	v_mfma_f32_16x16x32_bf16 v[68:71], v[186:189], v[230:233], v[68:71]
	v_mfma_f32_16x16x32_bf16 v[64:67], v[194:197], v[230:233], v[64:67]
	v_mfma_f32_16x16x32_bf16 v[116:119], v[190:193], v[206:209], v[116:119]
	v_mfma_f32_16x16x32_bf16 v[112:115], v[198:201], v[206:209], v[112:115]
	v_mfma_f32_16x16x32_bf16 v[100:103], v[190:193], v[214:217], v[100:103]
	v_mfma_f32_16x16x32_bf16 v[96:99], v[198:201], v[214:217], v[96:99]
	v_mfma_f32_16x16x32_bf16 v[84:87], v[190:193], v[222:225], v[84:87]
	v_mfma_f32_16x16x32_bf16 v[80:83], v[198:201], v[222:225], v[80:83]
	v_mfma_f32_16x16x32_bf16 v[68:71], v[190:193], v[234:237], v[68:71]
	v_mfma_f32_16x16x32_bf16 v[64:67], v[198:201], v[234:237], v[64:67]
	s_setprio 0
	s_barrier
	v_readfirstlane_b32 s26, v155
	v_lshl_add_u64 v[144:145], v[144:145], 0, s[6:7]
	s_mov_b32 m0, s26
	v_readfirstlane_b32 s26, v156
	s_add_u32 s24, s24, 0x40080
	ds_read_b128 v[202:205], v165 offset:49152
	ds_read_b128 v[206:209], v165 offset:50176
	ds_read_b128 v[210:213], v165 offset:51200
	ds_read_b128 v[214:217], v165 offset:52224
	ds_read_b128 v[218:221], v165 offset:53248
	ds_read_b128 v[222:225], v165 offset:54272
	ds_read_b128 v[230:233], v165 offset:55296
	ds_read_b128 v[234:237], v165 offset:56320
	global_load_lds_dwordx4 v[144:145], off
	v_lshl_add_u64 v[144:145], v[226:227], 0, s[6:7]
	s_mov_b32 m0, s26
	s_addc_u32 s25, s25, 0
	v_readfirstlane_b32 s26, v159
	global_load_lds_dwordx4 v[144:145], off
	v_lshl_add_u64 v[144:145], s[24:25], 0, v[130:131]
	s_mov_b32 m0, s26
	s_nop 0
	global_load_lds_dwordx4 v[144:145], off
	v_lshl_add_u64 v[144:145], s[24:25], 0, v[134:135]
	v_readfirstlane_b32 s24, v160
	s_mov_b32 m0, s24
	v_readfirstlane_b32 s24, v157
	global_load_lds_dwordx4 v[144:145], off
	v_lshl_add_u64 v[144:145], v[238:239], 0, s[6:7]
	s_mov_b32 m0, s24
	v_readfirstlane_b32 s24, v158
	global_load_lds_dwordx4 v[144:145], off
	v_lshl_add_u64 v[144:145], v[240:241], 0, s[6:7]
	s_mov_b32 m0, s24
	s_nop 0
	global_load_lds_dwordx4 v[144:145], off
	s_waitcnt vmcnt(8)
	s_waitcnt lgkmcnt(0)
	s_barrier
	s_setprio 1
	s_waitcnt lgkmcnt(0)
	v_mfma_f32_16x16x32_bf16 v[60:63], v[170:173], v[202:205], v[60:63]
	v_mfma_f32_16x16x32_bf16 v[56:59], v[178:181], v[202:205], v[56:59]
	v_mfma_f32_16x16x32_bf16 v[44:47], v[170:173], v[210:213], v[44:47]
	v_mfma_f32_16x16x32_bf16 v[40:43], v[178:181], v[210:213], v[40:43]
	v_mfma_f32_16x16x32_bf16 v[28:31], v[170:173], v[218:221], v[28:31]
	v_mfma_f32_16x16x32_bf16 v[24:27], v[178:181], v[218:221], v[24:27]
	v_mfma_f32_16x16x32_bf16 v[12:15], v[170:173], v[230:233], v[12:15]
	v_mfma_f32_16x16x32_bf16 v[8:11], v[178:181], v[230:233], v[8:11]
	v_mfma_f32_16x16x32_bf16 v[60:63], v[174:177], v[206:209], v[60:63]
	v_mfma_f32_16x16x32_bf16 v[56:59], v[182:185], v[206:209], v[56:59]
	v_mfma_f32_16x16x32_bf16 v[44:47], v[174:177], v[214:217], v[44:47]
	v_mfma_f32_16x16x32_bf16 v[40:43], v[182:185], v[214:217], v[40:43]
	v_mfma_f32_16x16x32_bf16 v[28:31], v[174:177], v[222:225], v[28:31]
	v_mfma_f32_16x16x32_bf16 v[24:27], v[182:185], v[222:225], v[24:27]
	v_mfma_f32_16x16x32_bf16 v[12:15], v[174:177], v[234:237], v[12:15]
	v_mfma_f32_16x16x32_bf16 v[8:11], v[182:185], v[234:237], v[8:11]
	s_setprio 0
	s_setprio 1
	v_mfma_f32_16x16x32_bf16 v[52:55], v[186:189], v[202:205], v[52:55]
	v_mfma_f32_16x16x32_bf16 v[48:51], v[194:197], v[202:205], v[48:51]
	v_mfma_f32_16x16x32_bf16 v[36:39], v[186:189], v[210:213], v[36:39]
	v_mfma_f32_16x16x32_bf16 v[32:35], v[194:197], v[210:213], v[32:35]
	v_mfma_f32_16x16x32_bf16 v[20:23], v[186:189], v[218:221], v[20:23]
	v_mfma_f32_16x16x32_bf16 v[16:19], v[194:197], v[218:221], v[16:19]
	v_mfma_f32_16x16x32_bf16 v[4:7], v[186:189], v[230:233], v[4:7]
	v_mfma_f32_16x16x32_bf16 v[0:3], v[194:197], v[230:233], v[0:3]
	v_mfma_f32_16x16x32_bf16 v[52:55], v[190:193], v[206:209], v[52:55]
	v_mfma_f32_16x16x32_bf16 v[48:51], v[198:201], v[206:209], v[48:51]
	v_mfma_f32_16x16x32_bf16 v[36:39], v[190:193], v[214:217], v[36:39]
	v_mfma_f32_16x16x32_bf16 v[32:35], v[198:201], v[214:217], v[32:35]
	v_mfma_f32_16x16x32_bf16 v[20:23], v[190:193], v[222:225], v[20:23]
	v_mfma_f32_16x16x32_bf16 v[16:19], v[198:201], v[222:225], v[16:19]
	v_mfma_f32_16x16x32_bf16 v[4:7], v[190:193], v[234:237], v[4:7]
	v_mfma_f32_16x16x32_bf16 v[0:3], v[198:201], v[234:237], v[0:3]
	s_setprio 0
	s_barrier
	s_add_i32 s42, s42, 2
	s_add_u32 s22, s22, 0x100
	s_addc_u32 s23, s23, 0
	s_add_u32 s40, s40, 0x100
	s_addc_u32 s41, s41, 0
.LBB0_1301:
	ds_read_b128 v[170:173], v163
	ds_read_b128 v[174:177], v163 offset:1024
	ds_read_b128 v[178:181], v163 offset:2048
	ds_read_b128 v[182:185], v163 offset:3072
	ds_read_b128 v[186:189], v164
	ds_read_b128 v[190:193], v164 offset:1024
	ds_read_b128 v[194:197], v164 offset:2048
	ds_read_b128 v[198:201], v164 offset:3072
	s_add_u32 s24, s22, 0xfffc0080
	s_addc_u32 s25, s23, -1
	s_cmp_eq_u32 s42, 12
	s_cselect_b32 s27, s15, s25
	s_cselect_b32 s26, s38, s24
	s_cselect_b32 s25, s13, s41
	s_cselect_b32 s24, s39, s40
	v_readfirstlane_b32 s43, v166
	v_lshl_add_u64 v[144:145], s[22:23], 0, v[136:137]
	s_mov_b32 m0, s43
	v_readfirstlane_b32 s43, v167
	ds_read_b128 v[202:205], v165
	ds_read_b128 v[206:209], v165 offset:1024
	ds_read_b128 v[210:213], v165 offset:2048
	ds_read_b128 v[214:217], v165 offset:3072
	ds_read_b128 v[218:221], v165 offset:4096
	ds_read_b128 v[222:225], v165 offset:5120
	ds_read_b128 v[230:233], v165 offset:6144
	ds_read_b128 v[234:237], v165 offset:7168
	global_load_lds_dwordx4 v[144:145], off
	v_lshl_add_u64 v[144:145], s[22:23], 0, v[138:139]
	s_mov_b32 m0, s43
	s_nop 0
	global_load_lds_dwordx4 v[144:145], off
	s_waitcnt vmcnt(8)
	s_waitcnt lgkmcnt(0)
	s_barrier
	s_setprio 1
	s_waitcnt lgkmcnt(0)
	v_mfma_f32_16x16x32_bf16 v[124:127], v[170:173], v[202:205], v[124:127]
	v_mfma_f32_16x16x32_bf16 v[120:123], v[178:181], v[202:205], v[120:123]
	v_mfma_f32_16x16x32_bf16 v[108:111], v[170:173], v[210:213], v[108:111]
	v_mfma_f32_16x16x32_bf16 v[104:107], v[178:181], v[210:213], v[104:107]
	v_mfma_f32_16x16x32_bf16 v[92:95], v[170:173], v[218:221], v[92:95]
	v_mfma_f32_16x16x32_bf16 v[88:91], v[178:181], v[218:221], v[88:91]
	v_mfma_f32_16x16x32_bf16 v[76:79], v[170:173], v[230:233], v[76:79]
	v_mfma_f32_16x16x32_bf16 v[72:75], v[178:181], v[230:233], v[72:75]
	v_mfma_f32_16x16x32_bf16 v[124:127], v[174:177], v[206:209], v[124:127]
	v_mfma_f32_16x16x32_bf16 v[120:123], v[182:185], v[206:209], v[120:123]
	v_mfma_f32_16x16x32_bf16 v[108:111], v[174:177], v[214:217], v[108:111]
	v_mfma_f32_16x16x32_bf16 v[104:107], v[182:185], v[214:217], v[104:107]
	v_mfma_f32_16x16x32_bf16 v[92:95], v[174:177], v[222:225], v[92:95]
	v_mfma_f32_16x16x32_bf16 v[88:91], v[182:185], v[222:225], v[88:91]
	v_mfma_f32_16x16x32_bf16 v[76:79], v[174:177], v[234:237], v[76:79]
	v_mfma_f32_16x16x32_bf16 v[72:75], v[182:185], v[234:237], v[72:75]
	s_setprio 0
	s_setprio 1
	v_mfma_f32_16x16x32_bf16 v[116:119], v[186:189], v[202:205], v[116:119]
	v_mfma_f32_16x16x32_bf16 v[112:115], v[194:197], v[202:205], v[112:115]
	v_mfma_f32_16x16x32_bf16 v[100:103], v[186:189], v[210:213], v[100:103]
	v_mfma_f32_16x16x32_bf16 v[96:99], v[194:197], v[210:213], v[96:99]
	v_mfma_f32_16x16x32_bf16 v[84:87], v[186:189], v[218:221], v[84:87]
	v_mfma_f32_16x16x32_bf16 v[80:83], v[194:197], v[218:221], v[80:83]
	v_mfma_f32_16x16x32_bf16 v[68:71], v[186:189], v[230:233], v[68:71]
	v_mfma_f32_16x16x32_bf16 v[64:67], v[194:197], v[230:233], v[64:67]
	v_mfma_f32_16x16x32_bf16 v[116:119], v[190:193], v[206:209], v[116:119]
	v_mfma_f32_16x16x32_bf16 v[112:115], v[198:201], v[206:209], v[112:115]
	v_mfma_f32_16x16x32_bf16 v[100:103], v[190:193], v[214:217], v[100:103]
	v_mfma_f32_16x16x32_bf16 v[96:99], v[198:201], v[214:217], v[96:99]
	v_mfma_f32_16x16x32_bf16 v[84:87], v[190:193], v[222:225], v[84:87]
	v_mfma_f32_16x16x32_bf16 v[80:83], v[198:201], v[222:225], v[80:83]
	v_mfma_f32_16x16x32_bf16 v[68:71], v[190:193], v[234:237], v[68:71]
	v_mfma_f32_16x16x32_bf16 v[64:67], v[198:201], v[234:237], v[64:67]
	s_setprio 0
	s_barrier
	v_readfirstlane_b32 s43, v147
	v_lshl_add_u64 v[144:145], s[24:25], 0, v[130:131]
	s_mov_b32 m0, s43
	v_readfirstlane_b32 s43, v148
	s_add_u32 s44, s24, 0x40000
	ds_read_b128 v[202:205], v165 offset:16384
	ds_read_b128 v[206:209], v165 offset:17408
	ds_read_b128 v[210:213], v165 offset:18432
	ds_read_b128 v[214:217], v165 offset:19456
	ds_read_b128 v[218:221], v165 offset:20480
	ds_read_b128 v[222:225], v165 offset:21504
	ds_read_b128 v[230:233], v165 offset:22528
	ds_read_b128 v[234:237], v165 offset:23552
	global_load_lds_dwordx4 v[144:145], off
	v_lshl_add_u64 v[226:227], s[24:25], 0, v[134:135]
	s_mov_b32 m0, s43
	s_addc_u32 s45, s25, 0
	v_readfirstlane_b32 s43, v149
	global_load_lds_dwordx4 v[226:227], off
	v_lshl_add_u64 v[238:239], s[44:45], 0, v[130:131]
	s_mov_b32 m0, s43
	v_readfirstlane_b32 s43, v150
	global_load_lds_dwordx4 v[238:239], off
	v_lshl_add_u64 v[238:239], s[44:45], 0, v[134:135]
	s_mov_b32 m0, s43
	v_readfirstlane_b32 s43, v151
	global_load_lds_dwordx4 v[238:239], off
	v_lshl_add_u64 v[238:239], s[26:27], 0, v[128:129]
	s_mov_b32 m0, s43
	v_readfirstlane_b32 s43, v152
	global_load_lds_dwordx4 v[238:239], off
	v_lshl_add_u64 v[240:241], s[26:27], 0, v[132:133]
	s_mov_b32 m0, s43
	s_nop 0
	global_load_lds_dwordx4 v[240:241], off
	s_waitcnt vmcnt(8)
	s_waitcnt lgkmcnt(0)
	s_barrier
	s_setprio 1
	s_waitcnt lgkmcnt(0)
	v_mfma_f32_16x16x32_bf16 v[60:63], v[170:173], v[202:205], v[60:63]
	v_mfma_f32_16x16x32_bf16 v[56:59], v[178:181], v[202:205], v[56:59]
	v_mfma_f32_16x16x32_bf16 v[44:47], v[170:173], v[210:213], v[44:47]
	v_mfma_f32_16x16x32_bf16 v[40:43], v[178:181], v[210:213], v[40:43]
	v_mfma_f32_16x16x32_bf16 v[28:31], v[170:173], v[218:221], v[28:31]
	v_mfma_f32_16x16x32_bf16 v[24:27], v[178:181], v[218:221], v[24:27]
	v_mfma_f32_16x16x32_bf16 v[12:15], v[170:173], v[230:233], v[12:15]
	v_mfma_f32_16x16x32_bf16 v[8:11], v[178:181], v[230:233], v[8:11]
	v_mfma_f32_16x16x32_bf16 v[60:63], v[174:177], v[206:209], v[60:63]
	v_mfma_f32_16x16x32_bf16 v[56:59], v[182:185], v[206:209], v[56:59]
	v_mfma_f32_16x16x32_bf16 v[44:47], v[174:177], v[214:217], v[44:47]
	v_mfma_f32_16x16x32_bf16 v[40:43], v[182:185], v[214:217], v[40:43]
	v_mfma_f32_16x16x32_bf16 v[28:31], v[174:177], v[222:225], v[28:31]
	v_mfma_f32_16x16x32_bf16 v[24:27], v[182:185], v[222:225], v[24:27]
	v_mfma_f32_16x16x32_bf16 v[12:15], v[174:177], v[234:237], v[12:15]
	v_mfma_f32_16x16x32_bf16 v[8:11], v[182:185], v[234:237], v[8:11]
	s_setprio 0
	s_setprio 1
	v_mfma_f32_16x16x32_bf16 v[52:55], v[186:189], v[202:205], v[52:55]
	v_mfma_f32_16x16x32_bf16 v[48:51], v[194:197], v[202:205], v[48:51]
	v_mfma_f32_16x16x32_bf16 v[36:39], v[186:189], v[210:213], v[36:39]
	v_mfma_f32_16x16x32_bf16 v[32:35], v[194:197], v[210:213], v[32:35]
	v_mfma_f32_16x16x32_bf16 v[20:23], v[186:189], v[218:221], v[20:23]
	v_mfma_f32_16x16x32_bf16 v[16:19], v[194:197], v[218:221], v[16:19]
	v_mfma_f32_16x16x32_bf16 v[4:7], v[186:189], v[230:233], v[4:7]
	v_mfma_f32_16x16x32_bf16 v[0:3], v[194:197], v[230:233], v[0:3]
	v_mfma_f32_16x16x32_bf16 v[52:55], v[190:193], v[206:209], v[52:55]
	v_mfma_f32_16x16x32_bf16 v[48:51], v[198:201], v[206:209], v[48:51]
	v_mfma_f32_16x16x32_bf16 v[36:39], v[190:193], v[214:217], v[36:39]
	v_mfma_f32_16x16x32_bf16 v[32:35], v[198:201], v[214:217], v[32:35]
	v_mfma_f32_16x16x32_bf16 v[20:23], v[190:193], v[222:225], v[20:23]
	v_mfma_f32_16x16x32_bf16 v[16:19], v[198:201], v[222:225], v[16:19]
	v_mfma_f32_16x16x32_bf16 v[4:7], v[190:193], v[234:237], v[4:7]
	v_mfma_f32_16x16x32_bf16 v[0:3], v[198:201], v[234:237], v[0:3]
	s_setprio 0
	s_barrier
	ds_read_b128 v[170:173], v168
	ds_read_b128 v[174:177], v168 offset:1024
	ds_read_b128 v[178:181], v168 offset:2048
	ds_read_b128 v[182:185], v168 offset:3072
	ds_read_b128 v[186:189], v169
	ds_read_b128 v[190:193], v169 offset:1024
	ds_read_b128 v[194:197], v169 offset:2048
	ds_read_b128 v[198:201], v169 offset:3072
	s_add_u32 s26, s26, 0x40000
	s_addc_u32 s27, s27, 0
	v_readfirstlane_b32 s43, v153
	v_lshl_add_u64 v[242:243], s[26:27], 0, v[128:129]
	s_mov_b32 m0, s43
	ds_read_b128 v[202:205], v165 offset:32768
	ds_read_b128 v[206:209], v165 offset:33792
	ds_read_b128 v[210:213], v165 offset:34816
	ds_read_b128 v[214:217], v165 offset:35840
	ds_read_b128 v[218:221], v165 offset:36864
	ds_read_b128 v[222:225], v165 offset:37888
	ds_read_b128 v[230:233], v165 offset:38912
	ds_read_b128 v[234:237], v165 offset:39936
	global_load_lds_dwordx4 v[242:243], off
	v_lshl_add_u64 v[242:243], s[26:27], 0, v[132:133]
	v_readfirstlane_b32 s26, v154
	s_mov_b32 m0, s26
	s_nop 0
	global_load_lds_dwordx4 v[242:243], off
	s_waitcnt vmcnt(8)
	s_waitcnt lgkmcnt(0)
	s_barrier
	s_setprio 1
	s_waitcnt lgkmcnt(0)
	v_mfma_f32_16x16x32_bf16 v[124:127], v[170:173], v[202:205], v[124:127]
	v_mfma_f32_16x16x32_bf16 v[120:123], v[178:181], v[202:205], v[120:123]
	v_mfma_f32_16x16x32_bf16 v[108:111], v[170:173], v[210:213], v[108:111]
	v_mfma_f32_16x16x32_bf16 v[104:107], v[178:181], v[210:213], v[104:107]
	v_mfma_f32_16x16x32_bf16 v[92:95], v[170:173], v[218:221], v[92:95]
	v_mfma_f32_16x16x32_bf16 v[88:91], v[178:181], v[218:221], v[88:91]
	v_mfma_f32_16x16x32_bf16 v[76:79], v[170:173], v[230:233], v[76:79]
	v_mfma_f32_16x16x32_bf16 v[72:75], v[178:181], v[230:233], v[72:75]
	v_mfma_f32_16x16x32_bf16 v[124:127], v[174:177], v[206:209], v[124:127]
	v_mfma_f32_16x16x32_bf16 v[120:123], v[182:185], v[206:209], v[120:123]
	v_mfma_f32_16x16x32_bf16 v[108:111], v[174:177], v[214:217], v[108:111]
	v_mfma_f32_16x16x32_bf16 v[104:107], v[182:185], v[214:217], v[104:107]
	v_mfma_f32_16x16x32_bf16 v[92:95], v[174:177], v[222:225], v[92:95]
	v_mfma_f32_16x16x32_bf16 v[88:91], v[182:185], v[222:225], v[88:91]
	v_mfma_f32_16x16x32_bf16 v[76:79], v[174:177], v[234:237], v[76:79]
	v_mfma_f32_16x16x32_bf16 v[72:75], v[182:185], v[234:237], v[72:75]
	s_setprio 0
	s_setprio 1
	v_mfma_f32_16x16x32_bf16 v[116:119], v[186:189], v[202:205], v[116:119]
	v_mfma_f32_16x16x32_bf16 v[112:115], v[194:197], v[202:205], v[112:115]
	v_mfma_f32_16x16x32_bf16 v[100:103], v[186:189], v[210:213], v[100:103]
	v_mfma_f32_16x16x32_bf16 v[96:99], v[194:197], v[210:213], v[96:99]
	v_mfma_f32_16x16x32_bf16 v[84:87], v[186:189], v[218:221], v[84:87]
	v_mfma_f32_16x16x32_bf16 v[80:83], v[194:197], v[218:221], v[80:83]
	v_mfma_f32_16x16x32_bf16 v[68:71], v[186:189], v[230:233], v[68:71]
	v_mfma_f32_16x16x32_bf16 v[64:67], v[194:197], v[230:233], v[64:67]
	v_mfma_f32_16x16x32_bf16 v[116:119], v[190:193], v[206:209], v[116:119]
	v_mfma_f32_16x16x32_bf16 v[112:115], v[198:201], v[206:209], v[112:115]
	v_mfma_f32_16x16x32_bf16 v[100:103], v[190:193], v[214:217], v[100:103]
	v_mfma_f32_16x16x32_bf16 v[96:99], v[198:201], v[214:217], v[96:99]
	v_mfma_f32_16x16x32_bf16 v[84:87], v[190:193], v[222:225], v[84:87]
	v_mfma_f32_16x16x32_bf16 v[80:83], v[198:201], v[222:225], v[80:83]
	v_mfma_f32_16x16x32_bf16 v[68:71], v[190:193], v[234:237], v[68:71]
	v_mfma_f32_16x16x32_bf16 v[64:67], v[198:201], v[234:237], v[64:67]
	s_setprio 0
	s_barrier
	v_readfirstlane_b32 s26, v155
	v_lshl_add_u64 v[144:145], v[144:145], 0, s[6:7]
	s_mov_b32 m0, s26
	v_readfirstlane_b32 s26, v156
	s_add_u32 s24, s24, 0x40080
	ds_read_b128 v[202:205], v165 offset:49152
	ds_read_b128 v[206:209], v165 offset:50176
	ds_read_b128 v[210:213], v165 offset:51200
	ds_read_b128 v[214:217], v165 offset:52224
	ds_read_b128 v[218:221], v165 offset:53248
	ds_read_b128 v[222:225], v165 offset:54272
	ds_read_b128 v[230:233], v165 offset:55296
	ds_read_b128 v[234:237], v165 offset:56320
	global_load_lds_dwordx4 v[144:145], off
	v_lshl_add_u64 v[144:145], v[226:227], 0, s[6:7]
	s_mov_b32 m0, s26
	s_addc_u32 s25, s25, 0
	v_readfirstlane_b32 s26, v159
	global_load_lds_dwordx4 v[144:145], off
	v_lshl_add_u64 v[144:145], s[24:25], 0, v[130:131]
	s_mov_b32 m0, s26
	s_nop 0
	global_load_lds_dwordx4 v[144:145], off
	v_lshl_add_u64 v[144:145], s[24:25], 0, v[134:135]
	v_readfirstlane_b32 s24, v160
	s_mov_b32 m0, s24
	v_readfirstlane_b32 s24, v157
	global_load_lds_dwordx4 v[144:145], off
	v_lshl_add_u64 v[144:145], v[238:239], 0, s[6:7]
	s_mov_b32 m0, s24
	v_readfirstlane_b32 s24, v158
	global_load_lds_dwordx4 v[144:145], off
	v_lshl_add_u64 v[144:145], v[240:241], 0, s[6:7]
	s_mov_b32 m0, s24
	s_nop 0
	global_load_lds_dwordx4 v[144:145], off
	s_waitcnt vmcnt(8)
	s_waitcnt lgkmcnt(0)
	s_barrier
	s_setprio 1
	s_waitcnt lgkmcnt(0)
	v_mfma_f32_16x16x32_bf16 v[60:63], v[170:173], v[202:205], v[60:63]
	v_mfma_f32_16x16x32_bf16 v[56:59], v[178:181], v[202:205], v[56:59]
	v_mfma_f32_16x16x32_bf16 v[44:47], v[170:173], v[210:213], v[44:47]
	v_mfma_f32_16x16x32_bf16 v[40:43], v[178:181], v[210:213], v[40:43]
	v_mfma_f32_16x16x32_bf16 v[28:31], v[170:173], v[218:221], v[28:31]
	v_mfma_f32_16x16x32_bf16 v[24:27], v[178:181], v[218:221], v[24:27]
	v_mfma_f32_16x16x32_bf16 v[12:15], v[170:173], v[230:233], v[12:15]
	v_mfma_f32_16x16x32_bf16 v[8:11], v[178:181], v[230:233], v[8:11]
	v_mfma_f32_16x16x32_bf16 v[60:63], v[174:177], v[206:209], v[60:63]
	v_mfma_f32_16x16x32_bf16 v[56:59], v[182:185], v[206:209], v[56:59]
	v_mfma_f32_16x16x32_bf16 v[44:47], v[174:177], v[214:217], v[44:47]
	v_mfma_f32_16x16x32_bf16 v[40:43], v[182:185], v[214:217], v[40:43]
	v_mfma_f32_16x16x32_bf16 v[28:31], v[174:177], v[222:225], v[28:31]
	v_mfma_f32_16x16x32_bf16 v[24:27], v[182:185], v[222:225], v[24:27]
	v_mfma_f32_16x16x32_bf16 v[12:15], v[174:177], v[234:237], v[12:15]
	v_mfma_f32_16x16x32_bf16 v[8:11], v[182:185], v[234:237], v[8:11]
	s_setprio 0
	s_setprio 1
	v_mfma_f32_16x16x32_bf16 v[52:55], v[186:189], v[202:205], v[52:55]
	v_mfma_f32_16x16x32_bf16 v[48:51], v[194:197], v[202:205], v[48:51]
	v_mfma_f32_16x16x32_bf16 v[36:39], v[186:189], v[210:213], v[36:39]
	v_mfma_f32_16x16x32_bf16 v[32:35], v[194:197], v[210:213], v[32:35]
	v_mfma_f32_16x16x32_bf16 v[20:23], v[186:189], v[218:221], v[20:23]
	v_mfma_f32_16x16x32_bf16 v[16:19], v[194:197], v[218:221], v[16:19]
	v_mfma_f32_16x16x32_bf16 v[4:7], v[186:189], v[230:233], v[4:7]
	v_mfma_f32_16x16x32_bf16 v[0:3], v[194:197], v[230:233], v[0:3]
	v_mfma_f32_16x16x32_bf16 v[52:55], v[190:193], v[206:209], v[52:55]
	v_mfma_f32_16x16x32_bf16 v[48:51], v[198:201], v[206:209], v[48:51]
	v_mfma_f32_16x16x32_bf16 v[36:39], v[190:193], v[214:217], v[36:39]
	v_mfma_f32_16x16x32_bf16 v[32:35], v[198:201], v[214:217], v[32:35]
	v_mfma_f32_16x16x32_bf16 v[20:23], v[190:193], v[222:225], v[20:23]
	v_mfma_f32_16x16x32_bf16 v[16:19], v[198:201], v[222:225], v[16:19]
	v_mfma_f32_16x16x32_bf16 v[4:7], v[190:193], v[234:237], v[4:7]
	v_mfma_f32_16x16x32_bf16 v[0:3], v[198:201], v[234:237], v[0:3]
	s_setprio 0
	s_barrier
	s_add_i32 s42, s42, 2
	s_add_u32 s22, s22, 0x100
	s_addc_u32 s23, s23, 0
	s_add_u32 s40, s40, 0x100
	s_addc_u32 s41, s41, 0
	s_cmp_gt_u32 s42, 13
	s_cbranch_scc0 .LBB0_1301
	s_add_u32 s100, s38, 0x40080
	s_addc_u32 s101, s15, 0
	v_readfirstlane_b32 s43, v166
	v_lshl_add_u64 v[144:145], s[100:101], 0, v[136:137]
	s_mov_b32 m0, s43
	v_readfirstlane_b32 s43, v167
	global_load_lds_dwordx4 v[144:145], off
	v_lshl_add_u64 v[144:145], s[100:101], 0, v[138:139]
	s_mov_b32 m0, s43
	s_nop 0
	global_load_lds_dwordx4 v[144:145], off
	s_and_b64 vcc, exec, s[8:9]
	s_cbranch_vccz .LBB0_1304
	s_barrier

.Lpeel_st_g1l1:
	s_waitcnt vmcnt(24)
	s_waitcnt lgkmcnt(0)
	s_barrier
	s_setprio 1
	s_waitcnt lgkmcnt(0)
	v_mfma_f32_16x16x32_bf16 v[124:127], v[170:173], v[202:205], 0
	v_mfma_f32_16x16x32_bf16 v[120:123], v[178:181], v[202:205], 0
	v_mfma_f32_16x16x32_bf16 v[116:119], v[170:173], v[210:213], 0
	v_mfma_f32_16x16x32_bf16 v[108:111], v[178:181], v[210:213], 0
	v_mfma_f32_16x16x32_bf16 v[100:103], v[170:173], v[218:221], 0
	v_mfma_f32_16x16x32_bf16 v[92:95], v[178:181], v[218:221], 0
	v_mfma_f32_16x16x32_bf16 v[84:87], v[170:173], v[230:233], 0
	v_mfma_f32_16x16x32_bf16 v[76:79], v[178:181], v[230:233], 0
	v_mfma_f32_16x16x32_bf16 v[124:127], v[174:177], v[206:209], v[124:127]
	v_mfma_f32_16x16x32_bf16 v[120:123], v[182:185], v[206:209], v[120:123]
	v_mfma_f32_16x16x32_bf16 v[116:119], v[174:177], v[214:217], v[116:119]
	v_mfma_f32_16x16x32_bf16 v[108:111], v[182:185], v[214:217], v[108:111]
	v_mfma_f32_16x16x32_bf16 v[100:103], v[174:177], v[222:225], v[100:103]
	v_mfma_f32_16x16x32_bf16 v[92:95], v[182:185], v[222:225], v[92:95]
	v_mfma_f32_16x16x32_bf16 v[84:87], v[174:177], v[234:237], v[84:87]
	v_mfma_f32_16x16x32_bf16 v[76:79], v[182:185], v[234:237], v[76:79]
	s_setprio 0
	s_setprio 1
	v_mfma_f32_16x16x32_bf16 v[112:115], v[186:189], v[202:205], 0
	v_mfma_f32_16x16x32_bf16 v[104:107], v[194:197], v[202:205], 0
	v_mfma_f32_16x16x32_bf16 v[96:99], v[186:189], v[210:213], 0
	v_mfma_f32_16x16x32_bf16 v[88:91], v[194:197], v[210:213], 0
	v_mfma_f32_16x16x32_bf16 v[80:83], v[186:189], v[218:221], 0
	v_mfma_f32_16x16x32_bf16 v[72:75], v[194:197], v[218:221], 0
	v_mfma_f32_16x16x32_bf16 v[68:71], v[186:189], v[230:233], 0
	v_mfma_f32_16x16x32_bf16 v[64:67], v[194:197], v[230:233], 0
	v_mfma_f32_16x16x32_bf16 v[112:115], v[190:193], v[206:209], v[112:115]
	v_mfma_f32_16x16x32_bf16 v[104:107], v[198:201], v[206:209], v[104:107]
	v_mfma_f32_16x16x32_bf16 v[96:99], v[190:193], v[214:217], v[96:99]
	v_mfma_f32_16x16x32_bf16 v[88:91], v[198:201], v[214:217], v[88:91]
	v_mfma_f32_16x16x32_bf16 v[80:83], v[190:193], v[222:225], v[80:83]
	v_mfma_f32_16x16x32_bf16 v[72:75], v[198:201], v[222:225], v[72:75]
	v_mfma_f32_16x16x32_bf16 v[68:71], v[190:193], v[234:237], v[68:71]
	v_mfma_f32_16x16x32_bf16 v[64:67], v[198:201], v[234:237], v[64:67]
	s_setprio 0
	s_barrier
	v_readfirstlane_b32 s42, v146
	v_lshl_add_u64 v[226:227], s[22:23], 0, v[130:131]
	s_mov_b32 m0, s42
	v_readfirstlane_b32 s42, v147
	ds_read_b128 v[202:205], v164 offset:16384
	ds_read_b128 v[206:209], v164 offset:17408
	ds_read_b128 v[210:213], v164 offset:18432
	ds_read_b128 v[214:217], v164 offset:19456
	ds_read_b128 v[218:221], v164 offset:20480
	ds_read_b128 v[222:225], v164 offset:21504
	ds_read_b128 v[230:233], v164 offset:22528
	ds_read_b128 v[234:237], v164 offset:23552
	global_load_lds_dwordx4 v[226:227], off
	s_mov_b32 m0, s42
	s_add_u32 s42, s22, 0x40000
	v_lshl_add_u64 v[228:229], s[22:23], 0, v[134:135]
	s_addc_u32 s43, s23, 0
	v_readfirstlane_b32 s44, v148
	global_load_lds_dwordx4 v[228:229], off
	v_lshl_add_u64 v[238:239], s[42:43], 0, v[130:131]
	s_mov_b32 m0, s44
	v_lshl_add_u64 v[240:241], s[24:25], 0, v[132:133]
	global_load_lds_dwordx4 v[238:239], off
	v_lshl_add_u64 v[238:239], s[42:43], 0, v[134:135]
	v_readfirstlane_b32 s42, v149
	s_mov_b32 m0, s42
	v_readfirstlane_b32 s42, v150
	global_load_lds_dwordx4 v[238:239], off
	v_lshl_add_u64 v[238:239], s[24:25], 0, v[128:129]
	s_mov_b32 m0, s42
	v_readfirstlane_b32 s42, v151
	global_load_lds_dwordx4 v[238:239], off
	s_mov_b32 m0, s42
	s_nop 0
	global_load_lds_dwordx4 v[240:241], off
	s_waitcnt vmcnt(24)
	s_cmp_lg_u32 s15, 1
	s_cbranch_scc1 .Lpeel_w2_g1l1
	s_waitcnt vmcnt(8)
.Lpeel_w2_g1l1:
	s_waitcnt lgkmcnt(0)
	s_barrier
	s_setprio 1
	s_waitcnt lgkmcnt(0)
	v_mfma_f32_16x16x32_bf16 v[60:63], v[170:173], v[202:205], 0
	v_mfma_f32_16x16x32_bf16 v[56:59], v[178:181], v[202:205], 0
	v_mfma_f32_16x16x32_bf16 v[52:55], v[170:173], v[210:213], 0
	v_mfma_f32_16x16x32_bf16 v[44:47], v[178:181], v[210:213], 0
	v_mfma_f32_16x16x32_bf16 v[36:39], v[170:173], v[218:221], 0
	v_mfma_f32_16x16x32_bf16 v[28:31], v[178:181], v[218:221], 0
	v_mfma_f32_16x16x32_bf16 v[20:23], v[170:173], v[230:233], 0
	v_mfma_f32_16x16x32_bf16 v[12:15], v[178:181], v[230:233], 0
	v_mfma_f32_16x16x32_bf16 v[60:63], v[174:177], v[206:209], v[60:63]
	v_mfma_f32_16x16x32_bf16 v[56:59], v[182:185], v[206:209], v[56:59]
	v_mfma_f32_16x16x32_bf16 v[52:55], v[174:177], v[214:217], v[52:55]
	v_mfma_f32_16x16x32_bf16 v[44:47], v[182:185], v[214:217], v[44:47]
	v_mfma_f32_16x16x32_bf16 v[36:39], v[174:177], v[222:225], v[36:39]
	v_mfma_f32_16x16x32_bf16 v[28:31], v[182:185], v[222:225], v[28:31]
	v_mfma_f32_16x16x32_bf16 v[20:23], v[174:177], v[234:237], v[20:23]
	v_mfma_f32_16x16x32_bf16 v[12:15], v[182:185], v[234:237], v[12:15]
	s_setprio 0
	s_setprio 1
	v_mfma_f32_16x16x32_bf16 v[48:51], v[186:189], v[202:205], 0
	v_mfma_f32_16x16x32_bf16 v[40:43], v[194:197], v[202:205], 0
	v_mfma_f32_16x16x32_bf16 v[32:35], v[186:189], v[210:213], 0
	v_mfma_f32_16x16x32_bf16 v[24:27], v[194:197], v[210:213], 0
	v_mfma_f32_16x16x32_bf16 v[16:19], v[186:189], v[218:221], 0
	v_mfma_f32_16x16x32_bf16 v[8:11], v[194:197], v[218:221], 0
	v_mfma_f32_16x16x32_bf16 v[4:7], v[186:189], v[230:233], 0
	v_mfma_f32_16x16x32_bf16 v[0:3], v[194:197], v[230:233], 0
	v_mfma_f32_16x16x32_bf16 v[48:51], v[190:193], v[206:209], v[48:51]
	v_mfma_f32_16x16x32_bf16 v[40:43], v[198:201], v[206:209], v[40:43]
	v_mfma_f32_16x16x32_bf16 v[32:35], v[190:193], v[214:217], v[32:35]
	v_mfma_f32_16x16x32_bf16 v[24:27], v[198:201], v[214:217], v[24:27]
	v_mfma_f32_16x16x32_bf16 v[16:19], v[190:193], v[222:225], v[16:19]
	v_mfma_f32_16x16x32_bf16 v[8:11], v[198:201], v[222:225], v[8:11]
	v_mfma_f32_16x16x32_bf16 v[4:7], v[190:193], v[234:237], v[4:7]
	v_mfma_f32_16x16x32_bf16 v[0:3], v[198:201], v[234:237], v[0:3]
	s_setprio 0
	s_barrier
	ds_read_b128 v[170:173], v167
	ds_read_b128 v[174:177], v167 offset:1024
	ds_read_b128 v[178:181], v167 offset:2048
	ds_read_b128 v[182:185], v167 offset:3072
	ds_read_b128 v[186:189], v168
	ds_read_b128 v[190:193], v168 offset:1024
	ds_read_b128 v[194:197], v168 offset:2048
	ds_read_b128 v[198:201], v168 offset:3072
	s_add_u32 s24, s24, 0x40000
	s_addc_u32 s25, s25, 0
	v_readfirstlane_b32 s42, v152
	v_lshl_add_u64 v[242:243], s[24:25], 0, v[128:129]
	s_mov_b32 m0, s42
	ds_read_b128 v[202:205], v164 offset:32768
	ds_read_b128 v[206:209], v164 offset:33792
	ds_read_b128 v[210:213], v164 offset:34816
	ds_read_b128 v[214:217], v164 offset:35840
	ds_read_b128 v[218:221], v164 offset:36864
	ds_read_b128 v[222:225], v164 offset:37888
	ds_read_b128 v[230:233], v164 offset:38912
	ds_read_b128 v[234:237], v164 offset:39936
	global_load_lds_dwordx4 v[242:243], off
	v_lshl_add_u64 v[242:243], s[24:25], 0, v[132:133]
	v_readfirstlane_b32 s24, v153
	s_mov_b32 m0, s24
	s_nop 0
	global_load_lds_dwordx4 v[242:243], off
	s_waitcnt vmcnt(24)
	s_cmp_lg_u32 s15, 1
	s_cbranch_scc1 .Lpeel_w3_g1l1
	s_waitcnt vmcnt(8)
.Lpeel_w3_g1l1:
	s_waitcnt lgkmcnt(0)
	s_barrier
	s_setprio 1
	s_waitcnt lgkmcnt(0)
	v_mfma_f32_16x16x32_bf16 v[124:127], v[170:173], v[202:205], v[124:127]
	v_mfma_f32_16x16x32_bf16 v[120:123], v[178:181], v[202:205], v[120:123]
	v_mfma_f32_16x16x32_bf16 v[116:119], v[170:173], v[210:213], v[116:119]
	v_mfma_f32_16x16x32_bf16 v[108:111], v[178:181], v[210:213], v[108:111]
	v_mfma_f32_16x16x32_bf16 v[100:103], v[170:173], v[218:221], v[100:103]
	v_mfma_f32_16x16x32_bf16 v[92:95], v[178:181], v[218:221], v[92:95]
	v_mfma_f32_16x16x32_bf16 v[84:87], v[170:173], v[230:233], v[84:87]
	v_mfma_f32_16x16x32_bf16 v[76:79], v[178:181], v[230:233], v[76:79]
	v_mfma_f32_16x16x32_bf16 v[124:127], v[174:177], v[206:209], v[124:127]
	v_mfma_f32_16x16x32_bf16 v[120:123], v[182:185], v[206:209], v[120:123]
	v_mfma_f32_16x16x32_bf16 v[116:119], v[174:177], v[214:217], v[116:119]
	v_mfma_f32_16x16x32_bf16 v[108:111], v[182:185], v[214:217], v[108:111]
	v_mfma_f32_16x16x32_bf16 v[100:103], v[174:177], v[222:225], v[100:103]
	v_mfma_f32_16x16x32_bf16 v[92:95], v[182:185], v[222:225], v[92:95]
	v_mfma_f32_16x16x32_bf16 v[84:87], v[174:177], v[234:237], v[84:87]
	v_mfma_f32_16x16x32_bf16 v[76:79], v[182:185], v[234:237], v[76:79]
	s_setprio 0
	s_setprio 1
	v_mfma_f32_16x16x32_bf16 v[112:115], v[186:189], v[202:205], v[112:115]
	v_mfma_f32_16x16x32_bf16 v[104:107], v[194:197], v[202:205], v[104:107]
	v_mfma_f32_16x16x32_bf16 v[96:99], v[186:189], v[210:213], v[96:99]
	v_mfma_f32_16x16x32_bf16 v[88:91], v[194:197], v[210:213], v[88:91]
	v_mfma_f32_16x16x32_bf16 v[80:83], v[186:189], v[218:221], v[80:83]
	v_mfma_f32_16x16x32_bf16 v[72:75], v[194:197], v[218:221], v[72:75]
	v_mfma_f32_16x16x32_bf16 v[68:71], v[186:189], v[230:233], v[68:71]
	v_mfma_f32_16x16x32_bf16 v[64:67], v[194:197], v[230:233], v[64:67]
	v_mfma_f32_16x16x32_bf16 v[112:115], v[190:193], v[206:209], v[112:115]
	v_mfma_f32_16x16x32_bf16 v[104:107], v[198:201], v[206:209], v[104:107]
	v_mfma_f32_16x16x32_bf16 v[96:99], v[190:193], v[214:217], v[96:99]
	v_mfma_f32_16x16x32_bf16 v[88:91], v[198:201], v[214:217], v[88:91]
	v_mfma_f32_16x16x32_bf16 v[80:83], v[190:193], v[222:225], v[80:83]
	v_mfma_f32_16x16x32_bf16 v[72:75], v[198:201], v[222:225], v[72:75]
	v_mfma_f32_16x16x32_bf16 v[68:71], v[190:193], v[234:237], v[68:71]
	v_mfma_f32_16x16x32_bf16 v[64:67], v[198:201], v[234:237], v[64:67]
	s_setprio 0
	s_barrier
	v_readfirstlane_b32 s24, v154
	v_lshl_add_u64 v[226:227], v[226:227], 0, s[6:7]
	s_mov_b32 m0, s24
	v_readfirstlane_b32 s24, v155
	s_add_u32 s22, s22, 0x40080
	ds_read_b128 v[202:205], v164 offset:49152
	ds_read_b128 v[206:209], v164 offset:50176
	ds_read_b128 v[210:213], v164 offset:51200
	ds_read_b128 v[214:217], v164 offset:52224
	ds_read_b128 v[218:221], v164 offset:53248
	ds_read_b128 v[222:225], v164 offset:54272
	ds_read_b128 v[230:233], v164 offset:55296
	ds_read_b128 v[234:237], v164 offset:56320
	global_load_lds_dwordx4 v[226:227], off
	v_lshl_add_u64 v[226:227], v[228:229], 0, s[6:7]
	s_mov_b32 m0, s24
	s_addc_u32 s23, s23, 0
	v_readfirstlane_b32 s24, v158
	global_load_lds_dwordx4 v[226:227], off
	v_lshl_add_u64 v[226:227], s[22:23], 0, v[130:131]
	s_mov_b32 m0, s24
	s_nop 0
	global_load_lds_dwordx4 v[226:227], off
	v_lshl_add_u64 v[226:227], s[22:23], 0, v[134:135]
	v_readfirstlane_b32 s22, v159
	s_mov_b32 m0, s22
	v_readfirstlane_b32 s22, v156
	global_load_lds_dwordx4 v[226:227], off
	v_lshl_add_u64 v[226:227], v[238:239], 0, s[6:7]
	s_mov_b32 m0, s22
	v_readfirstlane_b32 s22, v157
	global_load_lds_dwordx4 v[226:227], off
	v_lshl_add_u64 v[226:227], v[240:241], 0, s[6:7]
	s_mov_b32 m0, s22
	s_nop 0
	global_load_lds_dwordx4 v[226:227], off
	s_waitcnt vmcnt(8)
	s_waitcnt lgkmcnt(0)
	s_barrier
	s_setprio 1
	s_waitcnt lgkmcnt(0)
	v_mfma_f32_16x16x32_bf16 v[60:63], v[170:173], v[202:205], v[60:63]
	v_mfma_f32_16x16x32_bf16 v[56:59], v[178:181], v[202:205], v[56:59]
	v_mfma_f32_16x16x32_bf16 v[52:55], v[170:173], v[210:213], v[52:55]
	v_mfma_f32_16x16x32_bf16 v[44:47], v[178:181], v[210:213], v[44:47]
	v_mfma_f32_16x16x32_bf16 v[36:39], v[170:173], v[218:221], v[36:39]
	v_mfma_f32_16x16x32_bf16 v[28:31], v[178:181], v[218:221], v[28:31]
	v_mfma_f32_16x16x32_bf16 v[20:23], v[170:173], v[230:233], v[20:23]
	v_mfma_f32_16x16x32_bf16 v[12:15], v[178:181], v[230:233], v[12:15]
	v_mfma_f32_16x16x32_bf16 v[60:63], v[174:177], v[206:209], v[60:63]
	v_mfma_f32_16x16x32_bf16 v[56:59], v[182:185], v[206:209], v[56:59]
	v_mfma_f32_16x16x32_bf16 v[52:55], v[174:177], v[214:217], v[52:55]
	v_mfma_f32_16x16x32_bf16 v[44:47], v[182:185], v[214:217], v[44:47]
	v_mfma_f32_16x16x32_bf16 v[36:39], v[174:177], v[222:225], v[36:39]
	v_mfma_f32_16x16x32_bf16 v[28:31], v[182:185], v[222:225], v[28:31]
	v_mfma_f32_16x16x32_bf16 v[20:23], v[174:177], v[234:237], v[20:23]
	v_mfma_f32_16x16x32_bf16 v[12:15], v[182:185], v[234:237], v[12:15]
	s_setprio 0
	s_setprio 1
	v_mfma_f32_16x16x32_bf16 v[48:51], v[186:189], v[202:205], v[48:51]
	v_mfma_f32_16x16x32_bf16 v[40:43], v[194:197], v[202:205], v[40:43]
	v_mfma_f32_16x16x32_bf16 v[32:35], v[186:189], v[210:213], v[32:35]
	v_mfma_f32_16x16x32_bf16 v[24:27], v[194:197], v[210:213], v[24:27]
	v_mfma_f32_16x16x32_bf16 v[16:19], v[186:189], v[218:221], v[16:19]
	v_mfma_f32_16x16x32_bf16 v[8:11], v[194:197], v[218:221], v[8:11]
	v_mfma_f32_16x16x32_bf16 v[4:7], v[186:189], v[230:233], v[4:7]
	v_mfma_f32_16x16x32_bf16 v[0:3], v[194:197], v[230:233], v[0:3]
	v_mfma_f32_16x16x32_bf16 v[48:51], v[190:193], v[206:209], v[48:51]
	v_mfma_f32_16x16x32_bf16 v[40:43], v[198:201], v[206:209], v[40:43]
	v_mfma_f32_16x16x32_bf16 v[32:35], v[190:193], v[214:217], v[32:35]
	v_mfma_f32_16x16x32_bf16 v[24:27], v[198:201], v[214:217], v[24:27]
	v_mfma_f32_16x16x32_bf16 v[16:19], v[190:193], v[222:225], v[16:19]
	v_mfma_f32_16x16x32_bf16 v[8:11], v[198:201], v[222:225], v[8:11]
	v_mfma_f32_16x16x32_bf16 v[4:7], v[190:193], v[234:237], v[4:7]
	v_mfma_f32_16x16x32_bf16 v[0:3], v[198:201], v[234:237], v[0:3]
	s_setprio 0
	s_barrier
	s_add_i32 s41, s41, 2
	s_add_u32 s20, s20, 0x100
	s_addc_u32 s21, s21, 0
	s_add_u32 s39, s39, 0x100
	s_addc_u32 s40, s40, 0
.LBB0_1627:
	ds_read_b128 v[170:173], v162
	ds_read_b128 v[174:177], v162 offset:1024
	ds_read_b128 v[178:181], v162 offset:2048
	ds_read_b128 v[182:185], v162 offset:3072
	ds_read_b128 v[186:189], v163
	ds_read_b128 v[190:193], v163 offset:1024
	ds_read_b128 v[194:197], v163 offset:2048
	ds_read_b128 v[198:201], v163 offset:3072
	s_add_u32 s22, s20, 0xfffc0080
	s_addc_u32 s23, s21, -1
	s_cmp_eq_u32 s41, 12
	s_cselect_b32 s25, s13, s23
	s_cselect_b32 s24, s37, s22
	s_cselect_b32 s23, s11, s40
	s_cselect_b32 s22, s38, s39
	v_readfirstlane_b32 s42, v165
	v_lshl_add_u64 v[226:227], s[20:21], 0, v[136:137]
	s_mov_b32 m0, s42
	v_readfirstlane_b32 s42, v166
	ds_read_b128 v[202:205], v164
	ds_read_b128 v[206:209], v164 offset:1024
	ds_read_b128 v[210:213], v164 offset:2048
	ds_read_b128 v[214:217], v164 offset:3072
	ds_read_b128 v[218:221], v164 offset:4096
	ds_read_b128 v[222:225], v164 offset:5120
	ds_read_b128 v[230:233], v164 offset:6144
	ds_read_b128 v[234:237], v164 offset:7168
	global_load_lds_dwordx4 v[226:227], off
	v_lshl_add_u64 v[226:227], s[20:21], 0, v[138:139]
	s_mov_b32 m0, s42
	s_nop 0
	global_load_lds_dwordx4 v[226:227], off
	s_waitcnt vmcnt(8)
	s_waitcnt lgkmcnt(0)
	s_barrier
	s_setprio 1
	s_waitcnt lgkmcnt(0)
	v_mfma_f32_16x16x32_bf16 v[124:127], v[170:173], v[202:205], v[124:127]
	v_mfma_f32_16x16x32_bf16 v[120:123], v[178:181], v[202:205], v[120:123]
	v_mfma_f32_16x16x32_bf16 v[116:119], v[170:173], v[210:213], v[116:119]
	v_mfma_f32_16x16x32_bf16 v[108:111], v[178:181], v[210:213], v[108:111]
	v_mfma_f32_16x16x32_bf16 v[100:103], v[170:173], v[218:221], v[100:103]
	v_mfma_f32_16x16x32_bf16 v[92:95], v[178:181], v[218:221], v[92:95]
	v_mfma_f32_16x16x32_bf16 v[84:87], v[170:173], v[230:233], v[84:87]
	v_mfma_f32_16x16x32_bf16 v[76:79], v[178:181], v[230:233], v[76:79]
	v_mfma_f32_16x16x32_bf16 v[124:127], v[174:177], v[206:209], v[124:127]
	v_mfma_f32_16x16x32_bf16 v[120:123], v[182:185], v[206:209], v[120:123]
	v_mfma_f32_16x16x32_bf16 v[116:119], v[174:177], v[214:217], v[116:119]
	v_mfma_f32_16x16x32_bf16 v[108:111], v[182:185], v[214:217], v[108:111]
	v_mfma_f32_16x16x32_bf16 v[100:103], v[174:177], v[222:225], v[100:103]
	v_mfma_f32_16x16x32_bf16 v[92:95], v[182:185], v[222:225], v[92:95]
	v_mfma_f32_16x16x32_bf16 v[84:87], v[174:177], v[234:237], v[84:87]
	v_mfma_f32_16x16x32_bf16 v[76:79], v[182:185], v[234:237], v[76:79]
	s_setprio 0
	s_setprio 1
	v_mfma_f32_16x16x32_bf16 v[112:115], v[186:189], v[202:205], v[112:115]
	v_mfma_f32_16x16x32_bf16 v[104:107], v[194:197], v[202:205], v[104:107]
	v_mfma_f32_16x16x32_bf16 v[96:99], v[186:189], v[210:213], v[96:99]
	v_mfma_f32_16x16x32_bf16 v[88:91], v[194:197], v[210:213], v[88:91]
	v_mfma_f32_16x16x32_bf16 v[80:83], v[186:189], v[218:221], v[80:83]
	v_mfma_f32_16x16x32_bf16 v[72:75], v[194:197], v[218:221], v[72:75]
	v_mfma_f32_16x16x32_bf16 v[68:71], v[186:189], v[230:233], v[68:71]
	v_mfma_f32_16x16x32_bf16 v[64:67], v[194:197], v[230:233], v[64:67]
	v_mfma_f32_16x16x32_bf16 v[112:115], v[190:193], v[206:209], v[112:115]
	v_mfma_f32_16x16x32_bf16 v[104:107], v[198:201], v[206:209], v[104:107]
	v_mfma_f32_16x16x32_bf16 v[96:99], v[190:193], v[214:217], v[96:99]
	v_mfma_f32_16x16x32_bf16 v[88:91], v[198:201], v[214:217], v[88:91]
	v_mfma_f32_16x16x32_bf16 v[80:83], v[190:193], v[222:225], v[80:83]
	v_mfma_f32_16x16x32_bf16 v[72:75], v[198:201], v[222:225], v[72:75]
	v_mfma_f32_16x16x32_bf16 v[68:71], v[190:193], v[234:237], v[68:71]
	v_mfma_f32_16x16x32_bf16 v[64:67], v[198:201], v[234:237], v[64:67]
	s_setprio 0
	s_barrier
	v_readfirstlane_b32 s42, v146
	v_lshl_add_u64 v[226:227], s[22:23], 0, v[130:131]
	s_mov_b32 m0, s42
	v_readfirstlane_b32 s42, v147
	ds_read_b128 v[202:205], v164 offset:16384
	ds_read_b128 v[206:209], v164 offset:17408
	ds_read_b128 v[210:213], v164 offset:18432
	ds_read_b128 v[214:217], v164 offset:19456
	ds_read_b128 v[218:221], v164 offset:20480
	ds_read_b128 v[222:225], v164 offset:21504
	ds_read_b128 v[230:233], v164 offset:22528
	ds_read_b128 v[234:237], v164 offset:23552
	global_load_lds_dwordx4 v[226:227], off
	s_mov_b32 m0, s42
	s_add_u32 s42, s22, 0x40000
	v_lshl_add_u64 v[228:229], s[22:23], 0, v[134:135]
	s_addc_u32 s43, s23, 0
	v_readfirstlane_b32 s44, v148
	global_load_lds_dwordx4 v[228:229], off
	v_lshl_add_u64 v[238:239], s[42:43], 0, v[130:131]
	s_mov_b32 m0, s44
	v_lshl_add_u64 v[240:241], s[24:25], 0, v[132:133]
	global_load_lds_dwordx4 v[238:239], off
	v_lshl_add_u64 v[238:239], s[42:43], 0, v[134:135]
	v_readfirstlane_b32 s42, v149
	s_mov_b32 m0, s42
	v_readfirstlane_b32 s42, v150
	global_load_lds_dwordx4 v[238:239], off
	v_lshl_add_u64 v[238:239], s[24:25], 0, v[128:129]
	s_mov_b32 m0, s42
	v_readfirstlane_b32 s42, v151
	global_load_lds_dwordx4 v[238:239], off
	s_mov_b32 m0, s42
	s_nop 0
	global_load_lds_dwordx4 v[240:241], off
	s_waitcnt vmcnt(8)
	s_waitcnt lgkmcnt(0)
	s_barrier
	s_setprio 1
	s_waitcnt lgkmcnt(0)
	v_mfma_f32_16x16x32_bf16 v[60:63], v[170:173], v[202:205], v[60:63]
	v_mfma_f32_16x16x32_bf16 v[56:59], v[178:181], v[202:205], v[56:59]
	v_mfma_f32_16x16x32_bf16 v[52:55], v[170:173], v[210:213], v[52:55]
	v_mfma_f32_16x16x32_bf16 v[44:47], v[178:181], v[210:213], v[44:47]
	v_mfma_f32_16x16x32_bf16 v[36:39], v[170:173], v[218:221], v[36:39]
	v_mfma_f32_16x16x32_bf16 v[28:31], v[178:181], v[218:221], v[28:31]
	v_mfma_f32_16x16x32_bf16 v[20:23], v[170:173], v[230:233], v[20:23]
	v_mfma_f32_16x16x32_bf16 v[12:15], v[178:181], v[230:233], v[12:15]
	v_mfma_f32_16x16x32_bf16 v[60:63], v[174:177], v[206:209], v[60:63]
	v_mfma_f32_16x16x32_bf16 v[56:59], v[182:185], v[206:209], v[56:59]
	v_mfma_f32_16x16x32_bf16 v[52:55], v[174:177], v[214:217], v[52:55]
	v_mfma_f32_16x16x32_bf16 v[44:47], v[182:185], v[214:217], v[44:47]
	v_mfma_f32_16x16x32_bf16 v[36:39], v[174:177], v[222:225], v[36:39]
	v_mfma_f32_16x16x32_bf16 v[28:31], v[182:185], v[222:225], v[28:31]
	v_mfma_f32_16x16x32_bf16 v[20:23], v[174:177], v[234:237], v[20:23]
	v_mfma_f32_16x16x32_bf16 v[12:15], v[182:185], v[234:237], v[12:15]
	s_setprio 0
	s_setprio 1
	v_mfma_f32_16x16x32_bf16 v[48:51], v[186:189], v[202:205], v[48:51]
	v_mfma_f32_16x16x32_bf16 v[40:43], v[194:197], v[202:205], v[40:43]
	v_mfma_f32_16x16x32_bf16 v[32:35], v[186:189], v[210:213], v[32:35]
	v_mfma_f32_16x16x32_bf16 v[24:27], v[194:197], v[210:213], v[24:27]
	v_mfma_f32_16x16x32_bf16 v[16:19], v[186:189], v[218:221], v[16:19]
	v_mfma_f32_16x16x32_bf16 v[8:11], v[194:197], v[218:221], v[8:11]
	v_mfma_f32_16x16x32_bf16 v[4:7], v[186:189], v[230:233], v[4:7]
	v_mfma_f32_16x16x32_bf16 v[0:3], v[194:197], v[230:233], v[0:3]
	v_mfma_f32_16x16x32_bf16 v[48:51], v[190:193], v[206:209], v[48:51]
	v_mfma_f32_16x16x32_bf16 v[40:43], v[198:201], v[206:209], v[40:43]
	v_mfma_f32_16x16x32_bf16 v[32:35], v[190:193], v[214:217], v[32:35]
	v_mfma_f32_16x16x32_bf16 v[24:27], v[198:201], v[214:217], v[24:27]
	v_mfma_f32_16x16x32_bf16 v[16:19], v[190:193], v[222:225], v[16:19]
	v_mfma_f32_16x16x32_bf16 v[8:11], v[198:201], v[222:225], v[8:11]
	v_mfma_f32_16x16x32_bf16 v[4:7], v[190:193], v[234:237], v[4:7]
	v_mfma_f32_16x16x32_bf16 v[0:3], v[198:201], v[234:237], v[0:3]
	s_setprio 0
	s_barrier
	ds_read_b128 v[170:173], v167
	ds_read_b128 v[174:177], v167 offset:1024
	ds_read_b128 v[178:181], v167 offset:2048
	ds_read_b128 v[182:185], v167 offset:3072
	ds_read_b128 v[186:189], v168
	ds_read_b128 v[190:193], v168 offset:1024
	ds_read_b128 v[194:197], v168 offset:2048
	ds_read_b128 v[198:201], v168 offset:3072
	s_add_u32 s24, s24, 0x40000
	s_addc_u32 s25, s25, 0
	v_readfirstlane_b32 s42, v152
	v_lshl_add_u64 v[242:243], s[24:25], 0, v[128:129]
	s_mov_b32 m0, s42
	ds_read_b128 v[202:205], v164 offset:32768
	ds_read_b128 v[206:209], v164 offset:33792
	ds_read_b128 v[210:213], v164 offset:34816
	ds_read_b128 v[214:217], v164 offset:35840
	ds_read_b128 v[218:221], v164 offset:36864
	ds_read_b128 v[222:225], v164 offset:37888
	ds_read_b128 v[230:233], v164 offset:38912
	ds_read_b128 v[234:237], v164 offset:39936
	global_load_lds_dwordx4 v[242:243], off
	v_lshl_add_u64 v[242:243], s[24:25], 0, v[132:133]
	v_readfirstlane_b32 s24, v153
	s_mov_b32 m0, s24
	s_nop 0
	global_load_lds_dwordx4 v[242:243], off
	s_waitcnt vmcnt(8)
	s_waitcnt lgkmcnt(0)
	s_barrier
	s_setprio 1
	s_waitcnt lgkmcnt(0)
	v_mfma_f32_16x16x32_bf16 v[124:127], v[170:173], v[202:205], v[124:127]
	v_mfma_f32_16x16x32_bf16 v[120:123], v[178:181], v[202:205], v[120:123]
	v_mfma_f32_16x16x32_bf16 v[116:119], v[170:173], v[210:213], v[116:119]
	v_mfma_f32_16x16x32_bf16 v[108:111], v[178:181], v[210:213], v[108:111]
	v_mfma_f32_16x16x32_bf16 v[100:103], v[170:173], v[218:221], v[100:103]
	v_mfma_f32_16x16x32_bf16 v[92:95], v[178:181], v[218:221], v[92:95]
	v_mfma_f32_16x16x32_bf16 v[84:87], v[170:173], v[230:233], v[84:87]
	v_mfma_f32_16x16x32_bf16 v[76:79], v[178:181], v[230:233], v[76:79]
	v_mfma_f32_16x16x32_bf16 v[124:127], v[174:177], v[206:209], v[124:127]
	v_mfma_f32_16x16x32_bf16 v[120:123], v[182:185], v[206:209], v[120:123]
	v_mfma_f32_16x16x32_bf16 v[116:119], v[174:177], v[214:217], v[116:119]
	v_mfma_f32_16x16x32_bf16 v[108:111], v[182:185], v[214:217], v[108:111]
	v_mfma_f32_16x16x32_bf16 v[100:103], v[174:177], v[222:225], v[100:103]
	v_mfma_f32_16x16x32_bf16 v[92:95], v[182:185], v[222:225], v[92:95]
	v_mfma_f32_16x16x32_bf16 v[84:87], v[174:177], v[234:237], v[84:87]
	v_mfma_f32_16x16x32_bf16 v[76:79], v[182:185], v[234:237], v[76:79]
	s_setprio 0
	s_setprio 1
	v_mfma_f32_16x16x32_bf16 v[112:115], v[186:189], v[202:205], v[112:115]
	v_mfma_f32_16x16x32_bf16 v[104:107], v[194:197], v[202:205], v[104:107]
	v_mfma_f32_16x16x32_bf16 v[96:99], v[186:189], v[210:213], v[96:99]
	v_mfma_f32_16x16x32_bf16 v[88:91], v[194:197], v[210:213], v[88:91]
	v_mfma_f32_16x16x32_bf16 v[80:83], v[186:189], v[218:221], v[80:83]
	v_mfma_f32_16x16x32_bf16 v[72:75], v[194:197], v[218:221], v[72:75]
	v_mfma_f32_16x16x32_bf16 v[68:71], v[186:189], v[230:233], v[68:71]
	v_mfma_f32_16x16x32_bf16 v[64:67], v[194:197], v[230:233], v[64:67]
	v_mfma_f32_16x16x32_bf16 v[112:115], v[190:193], v[206:209], v[112:115]
	v_mfma_f32_16x16x32_bf16 v[104:107], v[198:201], v[206:209], v[104:107]
	v_mfma_f32_16x16x32_bf16 v[96:99], v[190:193], v[214:217], v[96:99]
	v_mfma_f32_16x16x32_bf16 v[88:91], v[198:201], v[214:217], v[88:91]
	v_mfma_f32_16x16x32_bf16 v[80:83], v[190:193], v[222:225], v[80:83]
	v_mfma_f32_16x16x32_bf16 v[72:75], v[198:201], v[222:225], v[72:75]
	v_mfma_f32_16x16x32_bf16 v[68:71], v[190:193], v[234:237], v[68:71]
	v_mfma_f32_16x16x32_bf16 v[64:67], v[198:201], v[234:237], v[64:67]
	s_setprio 0
	s_barrier
	v_readfirstlane_b32 s24, v154
	v_lshl_add_u64 v[226:227], v[226:227], 0, s[6:7]
	s_mov_b32 m0, s24
	v_readfirstlane_b32 s24, v155
	s_add_u32 s22, s22, 0x40080
	ds_read_b128 v[202:205], v164 offset:49152
	ds_read_b128 v[206:209], v164 offset:50176
	ds_read_b128 v[210:213], v164 offset:51200
	ds_read_b128 v[214:217], v164 offset:52224
	ds_read_b128 v[218:221], v164 offset:53248
	ds_read_b128 v[222:225], v164 offset:54272
	ds_read_b128 v[230:233], v164 offset:55296
	ds_read_b128 v[234:237], v164 offset:56320
	global_load_lds_dwordx4 v[226:227], off
	v_lshl_add_u64 v[226:227], v[228:229], 0, s[6:7]
	s_mov_b32 m0, s24
	s_addc_u32 s23, s23, 0
	v_readfirstlane_b32 s24, v158
	global_load_lds_dwordx4 v[226:227], off
	v_lshl_add_u64 v[226:227], s[22:23], 0, v[130:131]
	s_mov_b32 m0, s24
	s_nop 0
	global_load_lds_dwordx4 v[226:227], off
	v_lshl_add_u64 v[226:227], s[22:23], 0, v[134:135]
	v_readfirstlane_b32 s22, v159
	s_mov_b32 m0, s22
	v_readfirstlane_b32 s22, v156
	global_load_lds_dwordx4 v[226:227], off
	v_lshl_add_u64 v[226:227], v[238:239], 0, s[6:7]
	s_mov_b32 m0, s22
	v_readfirstlane_b32 s22, v157
	global_load_lds_dwordx4 v[226:227], off
	v_lshl_add_u64 v[226:227], v[240:241], 0, s[6:7]
	s_mov_b32 m0, s22
	s_nop 0
	global_load_lds_dwordx4 v[226:227], off
	s_waitcnt vmcnt(8)
	s_waitcnt lgkmcnt(0)
	s_barrier
	s_setprio 1
	s_waitcnt lgkmcnt(0)
	v_mfma_f32_16x16x32_bf16 v[60:63], v[170:173], v[202:205], v[60:63]
	v_mfma_f32_16x16x32_bf16 v[56:59], v[178:181], v[202:205], v[56:59]
	v_mfma_f32_16x16x32_bf16 v[52:55], v[170:173], v[210:213], v[52:55]
	v_mfma_f32_16x16x32_bf16 v[44:47], v[178:181], v[210:213], v[44:47]
	v_mfma_f32_16x16x32_bf16 v[36:39], v[170:173], v[218:221], v[36:39]
	v_mfma_f32_16x16x32_bf16 v[28:31], v[178:181], v[218:221], v[28:31]
	v_mfma_f32_16x16x32_bf16 v[20:23], v[170:173], v[230:233], v[20:23]
	v_mfma_f32_16x16x32_bf16 v[12:15], v[178:181], v[230:233], v[12:15]
	v_mfma_f32_16x16x32_bf16 v[60:63], v[174:177], v[206:209], v[60:63]
	v_mfma_f32_16x16x32_bf16 v[56:59], v[182:185], v[206:209], v[56:59]
	v_mfma_f32_16x16x32_bf16 v[52:55], v[174:177], v[214:217], v[52:55]
	v_mfma_f32_16x16x32_bf16 v[44:47], v[182:185], v[214:217], v[44:47]
	v_mfma_f32_16x16x32_bf16 v[36:39], v[174:177], v[222:225], v[36:39]
	v_mfma_f32_16x16x32_bf16 v[28:31], v[182:185], v[222:225], v[28:31]
	v_mfma_f32_16x16x32_bf16 v[20:23], v[174:177], v[234:237], v[20:23]
	v_mfma_f32_16x16x32_bf16 v[12:15], v[182:185], v[234:237], v[12:15]
	s_setprio 0
	s_setprio 1
	v_mfma_f32_16x16x32_bf16 v[48:51], v[186:189], v[202:205], v[48:51]
	v_mfma_f32_16x16x32_bf16 v[40:43], v[194:197], v[202:205], v[40:43]
	v_mfma_f32_16x16x32_bf16 v[32:35], v[186:189], v[210:213], v[32:35]
	v_mfma_f32_16x16x32_bf16 v[24:27], v[194:197], v[210:213], v[24:27]
	v_mfma_f32_16x16x32_bf16 v[16:19], v[186:189], v[218:221], v[16:19]
	v_mfma_f32_16x16x32_bf16 v[8:11], v[194:197], v[218:221], v[8:11]
	v_mfma_f32_16x16x32_bf16 v[4:7], v[186:189], v[230:233], v[4:7]
	v_mfma_f32_16x16x32_bf16 v[0:3], v[194:197], v[230:233], v[0:3]
	v_mfma_f32_16x16x32_bf16 v[48:51], v[190:193], v[206:209], v[48:51]
	v_mfma_f32_16x16x32_bf16 v[40:43], v[198:201], v[206:209], v[40:43]
	v_mfma_f32_16x16x32_bf16 v[32:35], v[190:193], v[214:217], v[32:35]
	v_mfma_f32_16x16x32_bf16 v[24:27], v[198:201], v[214:217], v[24:27]
	v_mfma_f32_16x16x32_bf16 v[16:19], v[190:193], v[222:225], v[16:19]
	v_mfma_f32_16x16x32_bf16 v[8:11], v[198:201], v[222:225], v[8:11]
	v_mfma_f32_16x16x32_bf16 v[4:7], v[190:193], v[234:237], v[4:7]
	v_mfma_f32_16x16x32_bf16 v[0:3], v[198:201], v[234:237], v[0:3]
	s_setprio 0
	s_barrier
	s_add_i32 s41, s41, 2
	s_add_u32 s20, s20, 0x100
	s_addc_u32 s21, s21, 0
	s_add_u32 s39, s39, 0x100
	s_addc_u32 s40, s40, 0
	s_cmp_gt_u32 s41, 13
	s_cbranch_scc0 .LBB0_1627
	s_add_u32 s100, s37, 0x40080
	s_addc_u32 s101, s13, 0
	v_readfirstlane_b32 s42, v165
	v_lshl_add_u64 v[226:227], s[100:101], 0, v[136:137]
	s_mov_b32 m0, s42
	v_readfirstlane_b32 s42, v166
	global_load_lds_dwordx4 v[226:227], off
	v_lshl_add_u64 v[226:227], s[100:101], 0, v[138:139]
	s_mov_b32 m0, s42
	s_nop 0
	global_load_lds_dwordx4 v[226:227], off
	s_and_b64 vcc, exec, s[8:9]
	s_cbranch_vccz .LBB0_1630
	s_barrier

.Lpeel_st_g3l1:
	s_waitcnt vmcnt(16)
	s_waitcnt lgkmcnt(0)
	s_barrier
	s_setprio 1
	s_waitcnt lgkmcnt(0)
	v_mfma_f32_16x16x32_bf16 v[124:127], v[170:173], v[202:205], 0
	v_mfma_f32_16x16x32_bf16 v[120:123], v[178:181], v[202:205], 0
	v_mfma_f32_16x16x32_bf16 v[108:111], v[170:173], v[210:213], 0
	v_mfma_f32_16x16x32_bf16 v[104:107], v[178:181], v[210:213], 0
	v_mfma_f32_16x16x32_bf16 v[92:95], v[170:173], v[218:221], 0
	v_mfma_f32_16x16x32_bf16 v[88:91], v[178:181], v[218:221], 0
	v_mfma_f32_16x16x32_bf16 v[76:79], v[170:173], v[230:233], 0
	v_mfma_f32_16x16x32_bf16 v[72:75], v[178:181], v[230:233], 0
	v_mfma_f32_16x16x32_bf16 v[124:127], v[174:177], v[206:209], v[124:127]
	v_mfma_f32_16x16x32_bf16 v[120:123], v[182:185], v[206:209], v[120:123]
	v_mfma_f32_16x16x32_bf16 v[108:111], v[174:177], v[214:217], v[108:111]
	v_mfma_f32_16x16x32_bf16 v[104:107], v[182:185], v[214:217], v[104:107]
	v_mfma_f32_16x16x32_bf16 v[92:95], v[174:177], v[222:225], v[92:95]
	v_mfma_f32_16x16x32_bf16 v[88:91], v[182:185], v[222:225], v[88:91]
	v_mfma_f32_16x16x32_bf16 v[76:79], v[174:177], v[234:237], v[76:79]
	v_mfma_f32_16x16x32_bf16 v[72:75], v[182:185], v[234:237], v[72:75]
	s_setprio 0
	s_setprio 1
	v_mfma_f32_16x16x32_bf16 v[116:119], v[186:189], v[202:205], 0
	v_mfma_f32_16x16x32_bf16 v[112:115], v[194:197], v[202:205], 0
	v_mfma_f32_16x16x32_bf16 v[100:103], v[186:189], v[210:213], 0
	v_mfma_f32_16x16x32_bf16 v[96:99], v[194:197], v[210:213], 0
	v_mfma_f32_16x16x32_bf16 v[84:87], v[186:189], v[218:221], 0
	v_mfma_f32_16x16x32_bf16 v[80:83], v[194:197], v[218:221], 0
	v_mfma_f32_16x16x32_bf16 v[68:71], v[186:189], v[230:233], 0
	v_mfma_f32_16x16x32_bf16 v[64:67], v[194:197], v[230:233], 0
	v_mfma_f32_16x16x32_bf16 v[116:119], v[190:193], v[206:209], v[116:119]
	v_mfma_f32_16x16x32_bf16 v[112:115], v[198:201], v[206:209], v[112:115]
	v_mfma_f32_16x16x32_bf16 v[100:103], v[190:193], v[214:217], v[100:103]
	v_mfma_f32_16x16x32_bf16 v[96:99], v[198:201], v[214:217], v[96:99]
	v_mfma_f32_16x16x32_bf16 v[84:87], v[190:193], v[222:225], v[84:87]
	v_mfma_f32_16x16x32_bf16 v[80:83], v[198:201], v[222:225], v[80:83]
	v_mfma_f32_16x16x32_bf16 v[68:71], v[190:193], v[234:237], v[68:71]
	v_mfma_f32_16x16x32_bf16 v[64:67], v[198:201], v[234:237], v[64:67]
	s_setprio 0
	s_barrier
	v_readfirstlane_b32 s43, v147
	v_lshl_add_u64 v[144:145], s[24:25], 0, v[130:131]
	s_mov_b32 m0, s43
	v_readfirstlane_b32 s43, v148
	s_add_u32 s44, s24, 0x40000
	ds_read_b128 v[202:205], v165 offset:16384
	ds_read_b128 v[206:209], v165 offset:17408
	ds_read_b128 v[210:213], v165 offset:18432
	ds_read_b128 v[214:217], v165 offset:19456
	ds_read_b128 v[218:221], v165 offset:20480
	ds_read_b128 v[222:225], v165 offset:21504
	ds_read_b128 v[230:233], v165 offset:22528
	ds_read_b128 v[234:237], v165 offset:23552
	global_load_lds_dwordx4 v[144:145], off
	v_lshl_add_u64 v[226:227], s[24:25], 0, v[134:135]
	s_mov_b32 m0, s43
	s_addc_u32 s45, s25, 0
	v_readfirstlane_b32 s43, v149
	global_load_lds_dwordx4 v[226:227], off
	v_lshl_add_u64 v[228:229], s[44:45], 0, v[130:131]
	s_mov_b32 m0, s43
	v_readfirstlane_b32 s43, v150
	global_load_lds_dwordx4 v[228:229], off
	v_lshl_add_u64 v[228:229], s[44:45], 0, v[134:135]
	s_mov_b32 m0, s43
	v_readfirstlane_b32 s43, v151
	global_load_lds_dwordx4 v[228:229], off
	v_lshl_add_u64 v[228:229], s[26:27], 0, v[128:129]
	s_mov_b32 m0, s43
	v_readfirstlane_b32 s43, v152
	global_load_lds_dwordx4 v[228:229], off
	v_lshl_add_u64 v[238:239], s[26:27], 0, v[132:133]
	s_mov_b32 m0, s43
	s_nop 0
	global_load_lds_dwordx4 v[238:239], off
	s_waitcnt vmcnt(16)
	s_cmp_lg_u32 s21, 1
	s_cbranch_scc1 .Lpeel_w2_g3l1
	s_waitcnt vmcnt(8)
.Lpeel_w2_g3l1:
	s_waitcnt lgkmcnt(0)
	s_barrier
	s_setprio 1
	s_waitcnt lgkmcnt(0)
	v_mfma_f32_16x16x32_bf16 v[60:63], v[170:173], v[202:205], 0
	v_mfma_f32_16x16x32_bf16 v[56:59], v[178:181], v[202:205], 0
	v_mfma_f32_16x16x32_bf16 v[44:47], v[170:173], v[210:213], 0
	v_mfma_f32_16x16x32_bf16 v[40:43], v[178:181], v[210:213], 0
	v_mfma_f32_16x16x32_bf16 v[28:31], v[170:173], v[218:221], 0
	v_mfma_f32_16x16x32_bf16 v[24:27], v[178:181], v[218:221], 0
	v_mfma_f32_16x16x32_bf16 v[12:15], v[170:173], v[230:233], 0
	v_mfma_f32_16x16x32_bf16 v[8:11], v[178:181], v[230:233], 0
	v_mfma_f32_16x16x32_bf16 v[60:63], v[174:177], v[206:209], v[60:63]
	v_mfma_f32_16x16x32_bf16 v[56:59], v[182:185], v[206:209], v[56:59]
	v_mfma_f32_16x16x32_bf16 v[44:47], v[174:177], v[214:217], v[44:47]
	v_mfma_f32_16x16x32_bf16 v[40:43], v[182:185], v[214:217], v[40:43]
	v_mfma_f32_16x16x32_bf16 v[28:31], v[174:177], v[222:225], v[28:31]
	v_mfma_f32_16x16x32_bf16 v[24:27], v[182:185], v[222:225], v[24:27]
	v_mfma_f32_16x16x32_bf16 v[12:15], v[174:177], v[234:237], v[12:15]
	v_mfma_f32_16x16x32_bf16 v[8:11], v[182:185], v[234:237], v[8:11]
	s_setprio 0
	s_setprio 1
	v_mfma_f32_16x16x32_bf16 v[52:55], v[186:189], v[202:205], 0
	v_mfma_f32_16x16x32_bf16 v[48:51], v[194:197], v[202:205], 0
	v_mfma_f32_16x16x32_bf16 v[36:39], v[186:189], v[210:213], 0
	v_mfma_f32_16x16x32_bf16 v[32:35], v[194:197], v[210:213], 0
	v_mfma_f32_16x16x32_bf16 v[20:23], v[186:189], v[218:221], 0
	v_mfma_f32_16x16x32_bf16 v[16:19], v[194:197], v[218:221], 0
	v_mfma_f32_16x16x32_bf16 v[4:7], v[186:189], v[230:233], 0
	v_mfma_f32_16x16x32_bf16 v[0:3], v[194:197], v[230:233], 0
	v_mfma_f32_16x16x32_bf16 v[52:55], v[190:193], v[206:209], v[52:55]
	v_mfma_f32_16x16x32_bf16 v[48:51], v[198:201], v[206:209], v[48:51]
	v_mfma_f32_16x16x32_bf16 v[36:39], v[190:193], v[214:217], v[36:39]
	v_mfma_f32_16x16x32_bf16 v[32:35], v[198:201], v[214:217], v[32:35]
	v_mfma_f32_16x16x32_bf16 v[20:23], v[190:193], v[222:225], v[20:23]
	v_mfma_f32_16x16x32_bf16 v[16:19], v[198:201], v[222:225], v[16:19]
	v_mfma_f32_16x16x32_bf16 v[4:7], v[190:193], v[234:237], v[4:7]
	v_mfma_f32_16x16x32_bf16 v[0:3], v[198:201], v[234:237], v[0:3]
	s_setprio 0
	s_barrier
	ds_read_b128 v[170:173], v168
	ds_read_b128 v[174:177], v168 offset:1024
	ds_read_b128 v[178:181], v168 offset:2048
	ds_read_b128 v[182:185], v168 offset:3072
	ds_read_b128 v[186:189], v169
	ds_read_b128 v[190:193], v169 offset:1024
	ds_read_b128 v[194:197], v169 offset:2048
	ds_read_b128 v[198:201], v169 offset:3072
	s_add_u32 s26, s26, 0x40000
	s_addc_u32 s27, s27, 0
	v_readfirstlane_b32 s43, v153
	v_lshl_add_u64 v[240:241], s[26:27], 0, v[128:129]
	s_mov_b32 m0, s43
	ds_read_b128 v[202:205], v165 offset:32768
	ds_read_b128 v[206:209], v165 offset:33792
	ds_read_b128 v[210:213], v165 offset:34816
	ds_read_b128 v[214:217], v165 offset:35840
	ds_read_b128 v[218:221], v165 offset:36864
	ds_read_b128 v[222:225], v165 offset:37888
	ds_read_b128 v[230:233], v165 offset:38912
	ds_read_b128 v[234:237], v165 offset:39936
	global_load_lds_dwordx4 v[240:241], off
	v_lshl_add_u64 v[240:241], s[26:27], 0, v[132:133]
	v_readfirstlane_b32 s26, v154
	s_mov_b32 m0, s26
	s_nop 0
	global_load_lds_dwordx4 v[240:241], off
	s_waitcnt vmcnt(16)
	s_cmp_lg_u32 s21, 1
	s_cbranch_scc1 .Lpeel_w3_g3l1
	s_waitcnt vmcnt(8)
.Lpeel_w3_g3l1:
	s_waitcnt lgkmcnt(0)
	s_barrier
	s_setprio 1
	s_waitcnt lgkmcnt(0)
	v_mfma_f32_16x16x32_bf16 v[124:127], v[170:173], v[202:205], v[124:127]
	v_mfma_f32_16x16x32_bf16 v[120:123], v[178:181], v[202:205], v[120:123]
	v_mfma_f32_16x16x32_bf16 v[108:111], v[170:173], v[210:213], v[108:111]
	v_mfma_f32_16x16x32_bf16 v[104:107], v[178:181], v[210:213], v[104:107]
	v_mfma_f32_16x16x32_bf16 v[92:95], v[170:173], v[218:221], v[92:95]
	v_mfma_f32_16x16x32_bf16 v[88:91], v[178:181], v[218:221], v[88:91]
	v_mfma_f32_16x16x32_bf16 v[76:79], v[170:173], v[230:233], v[76:79]
	v_mfma_f32_16x16x32_bf16 v[72:75], v[178:181], v[230:233], v[72:75]
	v_mfma_f32_16x16x32_bf16 v[124:127], v[174:177], v[206:209], v[124:127]
	v_mfma_f32_16x16x32_bf16 v[120:123], v[182:185], v[206:209], v[120:123]
	v_mfma_f32_16x16x32_bf16 v[108:111], v[174:177], v[214:217], v[108:111]
	v_mfma_f32_16x16x32_bf16 v[104:107], v[182:185], v[214:217], v[104:107]
	v_mfma_f32_16x16x32_bf16 v[92:95], v[174:177], v[222:225], v[92:95]
	v_mfma_f32_16x16x32_bf16 v[88:91], v[182:185], v[222:225], v[88:91]
	v_mfma_f32_16x16x32_bf16 v[76:79], v[174:177], v[234:237], v[76:79]
	v_mfma_f32_16x16x32_bf16 v[72:75], v[182:185], v[234:237], v[72:75]
	s_setprio 0
	s_setprio 1
	v_mfma_f32_16x16x32_bf16 v[116:119], v[186:189], v[202:205], v[116:119]
	v_mfma_f32_16x16x32_bf16 v[112:115], v[194:197], v[202:205], v[112:115]
	v_mfma_f32_16x16x32_bf16 v[100:103], v[186:189], v[210:213], v[100:103]
	v_mfma_f32_16x16x32_bf16 v[96:99], v[194:197], v[210:213], v[96:99]
	v_mfma_f32_16x16x32_bf16 v[84:87], v[186:189], v[218:221], v[84:87]
	v_mfma_f32_16x16x32_bf16 v[80:83], v[194:197], v[218:221], v[80:83]
	v_mfma_f32_16x16x32_bf16 v[68:71], v[186:189], v[230:233], v[68:71]
	v_mfma_f32_16x16x32_bf16 v[64:67], v[194:197], v[230:233], v[64:67]
	v_mfma_f32_16x16x32_bf16 v[116:119], v[190:193], v[206:209], v[116:119]
	v_mfma_f32_16x16x32_bf16 v[112:115], v[198:201], v[206:209], v[112:115]
	v_mfma_f32_16x16x32_bf16 v[100:103], v[190:193], v[214:217], v[100:103]
	v_mfma_f32_16x16x32_bf16 v[96:99], v[198:201], v[214:217], v[96:99]
	v_mfma_f32_16x16x32_bf16 v[84:87], v[190:193], v[222:225], v[84:87]
	v_mfma_f32_16x16x32_bf16 v[80:83], v[198:201], v[222:225], v[80:83]
	v_mfma_f32_16x16x32_bf16 v[68:71], v[190:193], v[234:237], v[68:71]
	v_mfma_f32_16x16x32_bf16 v[64:67], v[198:201], v[234:237], v[64:67]
	s_setprio 0
	s_barrier
	v_readfirstlane_b32 s26, v155
	v_lshl_add_u64 v[144:145], v[144:145], 0, s[6:7]
	s_mov_b32 m0, s26
	v_readfirstlane_b32 s26, v156
	s_add_u32 s24, s24, 0x40080
	ds_read_b128 v[202:205], v165 offset:49152
	ds_read_b128 v[206:209], v165 offset:50176
	ds_read_b128 v[210:213], v165 offset:51200
	ds_read_b128 v[214:217], v165 offset:52224
	ds_read_b128 v[218:221], v165 offset:53248
	ds_read_b128 v[222:225], v165 offset:54272
	ds_read_b128 v[230:233], v165 offset:55296
	ds_read_b128 v[234:237], v165 offset:56320
	global_load_lds_dwordx4 v[144:145], off
	v_lshl_add_u64 v[144:145], v[226:227], 0, s[6:7]
	s_mov_b32 m0, s26
	s_addc_u32 s25, s25, 0
	v_readfirstlane_b32 s26, v159
	global_load_lds_dwordx4 v[144:145], off
	v_lshl_add_u64 v[144:145], s[24:25], 0, v[130:131]
	s_mov_b32 m0, s26
	s_nop 0
	global_load_lds_dwordx4 v[144:145], off
	v_lshl_add_u64 v[144:145], s[24:25], 0, v[134:135]
	v_readfirstlane_b32 s24, v160
	s_mov_b32 m0, s24
	v_readfirstlane_b32 s24, v157
	global_load_lds_dwordx4 v[144:145], off
	v_lshl_add_u64 v[144:145], v[228:229], 0, s[6:7]
	s_mov_b32 m0, s24
	v_readfirstlane_b32 s24, v158
	global_load_lds_dwordx4 v[144:145], off
	v_lshl_add_u64 v[144:145], v[238:239], 0, s[6:7]
	s_mov_b32 m0, s24
	s_nop 0
	global_load_lds_dwordx4 v[144:145], off
	s_waitcnt vmcnt(8)
	s_waitcnt lgkmcnt(0)
	s_barrier
	s_setprio 1
	s_waitcnt lgkmcnt(0)
	v_mfma_f32_16x16x32_bf16 v[60:63], v[170:173], v[202:205], v[60:63]
	v_mfma_f32_16x16x32_bf16 v[56:59], v[178:181], v[202:205], v[56:59]
	v_mfma_f32_16x16x32_bf16 v[44:47], v[170:173], v[210:213], v[44:47]
	v_mfma_f32_16x16x32_bf16 v[40:43], v[178:181], v[210:213], v[40:43]
	v_mfma_f32_16x16x32_bf16 v[28:31], v[170:173], v[218:221], v[28:31]
	v_mfma_f32_16x16x32_bf16 v[24:27], v[178:181], v[218:221], v[24:27]
	v_mfma_f32_16x16x32_bf16 v[12:15], v[170:173], v[230:233], v[12:15]
	v_mfma_f32_16x16x32_bf16 v[8:11], v[178:181], v[230:233], v[8:11]
	v_mfma_f32_16x16x32_bf16 v[60:63], v[174:177], v[206:209], v[60:63]
	v_mfma_f32_16x16x32_bf16 v[56:59], v[182:185], v[206:209], v[56:59]
	v_mfma_f32_16x16x32_bf16 v[44:47], v[174:177], v[214:217], v[44:47]
	v_mfma_f32_16x16x32_bf16 v[40:43], v[182:185], v[214:217], v[40:43]
	v_mfma_f32_16x16x32_bf16 v[28:31], v[174:177], v[222:225], v[28:31]
	v_mfma_f32_16x16x32_bf16 v[24:27], v[182:185], v[222:225], v[24:27]
	v_mfma_f32_16x16x32_bf16 v[12:15], v[174:177], v[234:237], v[12:15]
	v_mfma_f32_16x16x32_bf16 v[8:11], v[182:185], v[234:237], v[8:11]
	s_setprio 0
	s_setprio 1
	v_mfma_f32_16x16x32_bf16 v[52:55], v[186:189], v[202:205], v[52:55]
	v_mfma_f32_16x16x32_bf16 v[48:51], v[194:197], v[202:205], v[48:51]
	v_mfma_f32_16x16x32_bf16 v[36:39], v[186:189], v[210:213], v[36:39]
	v_mfma_f32_16x16x32_bf16 v[32:35], v[194:197], v[210:213], v[32:35]
	v_mfma_f32_16x16x32_bf16 v[20:23], v[186:189], v[218:221], v[20:23]
	v_mfma_f32_16x16x32_bf16 v[16:19], v[194:197], v[218:221], v[16:19]
	v_mfma_f32_16x16x32_bf16 v[4:7], v[186:189], v[230:233], v[4:7]
	v_mfma_f32_16x16x32_bf16 v[0:3], v[194:197], v[230:233], v[0:3]
	v_mfma_f32_16x16x32_bf16 v[52:55], v[190:193], v[206:209], v[52:55]
	v_mfma_f32_16x16x32_bf16 v[48:51], v[198:201], v[206:209], v[48:51]
	v_mfma_f32_16x16x32_bf16 v[36:39], v[190:193], v[214:217], v[36:39]
	v_mfma_f32_16x16x32_bf16 v[32:35], v[198:201], v[214:217], v[32:35]
	v_mfma_f32_16x16x32_bf16 v[20:23], v[190:193], v[222:225], v[20:23]
	v_mfma_f32_16x16x32_bf16 v[16:19], v[198:201], v[222:225], v[16:19]
	v_mfma_f32_16x16x32_bf16 v[4:7], v[190:193], v[234:237], v[4:7]
	v_mfma_f32_16x16x32_bf16 v[0:3], v[198:201], v[234:237], v[0:3]
	s_setprio 0
	s_barrier
	s_add_i32 s42, s42, 2
	s_add_u32 s22, s22, 0x100
	s_addc_u32 s23, s23, 0
	s_add_u32 s40, s40, 0x100
	s_addc_u32 s41, s41, 0
.LBB0_2729:
	ds_read_b128 v[170:173], v163
	ds_read_b128 v[174:177], v163 offset:1024
	ds_read_b128 v[178:181], v163 offset:2048
	ds_read_b128 v[182:185], v163 offset:3072
	ds_read_b128 v[186:189], v164
	ds_read_b128 v[190:193], v164 offset:1024
	ds_read_b128 v[194:197], v164 offset:2048
	ds_read_b128 v[198:201], v164 offset:3072
	s_add_u32 s24, s22, 0xfffc0080
	s_addc_u32 s25, s23, -1
	s_cmp_eq_u32 s42, 12
	s_cselect_b32 s27, s15, s25
	s_cselect_b32 s26, s38, s24
	s_cselect_b32 s25, s13, s41
	s_cselect_b32 s24, s39, s40
	v_readfirstlane_b32 s43, v166
	v_lshl_add_u64 v[144:145], s[22:23], 0, v[136:137]
	s_mov_b32 m0, s43
	v_readfirstlane_b32 s43, v167
	ds_read_b128 v[202:205], v165
	ds_read_b128 v[206:209], v165 offset:1024
	ds_read_b128 v[210:213], v165 offset:2048
	ds_read_b128 v[214:217], v165 offset:3072
	ds_read_b128 v[218:221], v165 offset:4096
	ds_read_b128 v[222:225], v165 offset:5120
	ds_read_b128 v[230:233], v165 offset:6144
	ds_read_b128 v[234:237], v165 offset:7168
	global_load_lds_dwordx4 v[144:145], off
	v_lshl_add_u64 v[144:145], s[22:23], 0, v[138:139]
	s_mov_b32 m0, s43
	s_nop 0
	global_load_lds_dwordx4 v[144:145], off
	s_waitcnt vmcnt(8)
	s_waitcnt lgkmcnt(0)
	s_barrier
	s_setprio 1
	s_waitcnt lgkmcnt(0)
	v_mfma_f32_16x16x32_bf16 v[124:127], v[170:173], v[202:205], v[124:127]
	v_mfma_f32_16x16x32_bf16 v[120:123], v[178:181], v[202:205], v[120:123]
	v_mfma_f32_16x16x32_bf16 v[108:111], v[170:173], v[210:213], v[108:111]
	v_mfma_f32_16x16x32_bf16 v[104:107], v[178:181], v[210:213], v[104:107]
	v_mfma_f32_16x16x32_bf16 v[92:95], v[170:173], v[218:221], v[92:95]
	v_mfma_f32_16x16x32_bf16 v[88:91], v[178:181], v[218:221], v[88:91]
	v_mfma_f32_16x16x32_bf16 v[76:79], v[170:173], v[230:233], v[76:79]
	v_mfma_f32_16x16x32_bf16 v[72:75], v[178:181], v[230:233], v[72:75]
	v_mfma_f32_16x16x32_bf16 v[124:127], v[174:177], v[206:209], v[124:127]
	v_mfma_f32_16x16x32_bf16 v[120:123], v[182:185], v[206:209], v[120:123]
	v_mfma_f32_16x16x32_bf16 v[108:111], v[174:177], v[214:217], v[108:111]
	v_mfma_f32_16x16x32_bf16 v[104:107], v[182:185], v[214:217], v[104:107]
	v_mfma_f32_16x16x32_bf16 v[92:95], v[174:177], v[222:225], v[92:95]
	v_mfma_f32_16x16x32_bf16 v[88:91], v[182:185], v[222:225], v[88:91]
	v_mfma_f32_16x16x32_bf16 v[76:79], v[174:177], v[234:237], v[76:79]
	v_mfma_f32_16x16x32_bf16 v[72:75], v[182:185], v[234:237], v[72:75]
	s_setprio 0
	s_setprio 1
	v_mfma_f32_16x16x32_bf16 v[116:119], v[186:189], v[202:205], v[116:119]
	v_mfma_f32_16x16x32_bf16 v[112:115], v[194:197], v[202:205], v[112:115]
	v_mfma_f32_16x16x32_bf16 v[100:103], v[186:189], v[210:213], v[100:103]
	v_mfma_f32_16x16x32_bf16 v[96:99], v[194:197], v[210:213], v[96:99]
	v_mfma_f32_16x16x32_bf16 v[84:87], v[186:189], v[218:221], v[84:87]
	v_mfma_f32_16x16x32_bf16 v[80:83], v[194:197], v[218:221], v[80:83]
	v_mfma_f32_16x16x32_bf16 v[68:71], v[186:189], v[230:233], v[68:71]
	v_mfma_f32_16x16x32_bf16 v[64:67], v[194:197], v[230:233], v[64:67]
	v_mfma_f32_16x16x32_bf16 v[116:119], v[190:193], v[206:209], v[116:119]
	v_mfma_f32_16x16x32_bf16 v[112:115], v[198:201], v[206:209], v[112:115]
	v_mfma_f32_16x16x32_bf16 v[100:103], v[190:193], v[214:217], v[100:103]
	v_mfma_f32_16x16x32_bf16 v[96:99], v[198:201], v[214:217], v[96:99]
	v_mfma_f32_16x16x32_bf16 v[84:87], v[190:193], v[222:225], v[84:87]
	v_mfma_f32_16x16x32_bf16 v[80:83], v[198:201], v[222:225], v[80:83]
	v_mfma_f32_16x16x32_bf16 v[68:71], v[190:193], v[234:237], v[68:71]
	v_mfma_f32_16x16x32_bf16 v[64:67], v[198:201], v[234:237], v[64:67]
	s_setprio 0
	s_barrier
	v_readfirstlane_b32 s43, v147
	v_lshl_add_u64 v[144:145], s[24:25], 0, v[130:131]
	s_mov_b32 m0, s43
	v_readfirstlane_b32 s43, v148
	s_add_u32 s44, s24, 0x40000
	ds_read_b128 v[202:205], v165 offset:16384
	ds_read_b128 v[206:209], v165 offset:17408
	ds_read_b128 v[210:213], v165 offset:18432
	ds_read_b128 v[214:217], v165 offset:19456
	ds_read_b128 v[218:221], v165 offset:20480
	ds_read_b128 v[222:225], v165 offset:21504
	ds_read_b128 v[230:233], v165 offset:22528
	ds_read_b128 v[234:237], v165 offset:23552
	global_load_lds_dwordx4 v[144:145], off
	v_lshl_add_u64 v[226:227], s[24:25], 0, v[134:135]
	s_mov_b32 m0, s43
	s_addc_u32 s45, s25, 0
	v_readfirstlane_b32 s43, v149
	global_load_lds_dwordx4 v[226:227], off
	v_lshl_add_u64 v[228:229], s[44:45], 0, v[130:131]
	s_mov_b32 m0, s43
	v_readfirstlane_b32 s43, v150
	global_load_lds_dwordx4 v[228:229], off
	v_lshl_add_u64 v[228:229], s[44:45], 0, v[134:135]
	s_mov_b32 m0, s43
	v_readfirstlane_b32 s43, v151
	global_load_lds_dwordx4 v[228:229], off
	v_lshl_add_u64 v[228:229], s[26:27], 0, v[128:129]
	s_mov_b32 m0, s43
	v_readfirstlane_b32 s43, v152
	global_load_lds_dwordx4 v[228:229], off
	v_lshl_add_u64 v[238:239], s[26:27], 0, v[132:133]
	s_mov_b32 m0, s43
	s_nop 0
	global_load_lds_dwordx4 v[238:239], off
	s_waitcnt vmcnt(8)
	s_waitcnt lgkmcnt(0)
	s_barrier
	s_setprio 1
	s_waitcnt lgkmcnt(0)
	v_mfma_f32_16x16x32_bf16 v[60:63], v[170:173], v[202:205], v[60:63]
	v_mfma_f32_16x16x32_bf16 v[56:59], v[178:181], v[202:205], v[56:59]
	v_mfma_f32_16x16x32_bf16 v[44:47], v[170:173], v[210:213], v[44:47]
	v_mfma_f32_16x16x32_bf16 v[40:43], v[178:181], v[210:213], v[40:43]
	v_mfma_f32_16x16x32_bf16 v[28:31], v[170:173], v[218:221], v[28:31]
	v_mfma_f32_16x16x32_bf16 v[24:27], v[178:181], v[218:221], v[24:27]
	v_mfma_f32_16x16x32_bf16 v[12:15], v[170:173], v[230:233], v[12:15]
	v_mfma_f32_16x16x32_bf16 v[8:11], v[178:181], v[230:233], v[8:11]
	v_mfma_f32_16x16x32_bf16 v[60:63], v[174:177], v[206:209], v[60:63]
	v_mfma_f32_16x16x32_bf16 v[56:59], v[182:185], v[206:209], v[56:59]
	v_mfma_f32_16x16x32_bf16 v[44:47], v[174:177], v[214:217], v[44:47]
	v_mfma_f32_16x16x32_bf16 v[40:43], v[182:185], v[214:217], v[40:43]
	v_mfma_f32_16x16x32_bf16 v[28:31], v[174:177], v[222:225], v[28:31]
	v_mfma_f32_16x16x32_bf16 v[24:27], v[182:185], v[222:225], v[24:27]
	v_mfma_f32_16x16x32_bf16 v[12:15], v[174:177], v[234:237], v[12:15]
	v_mfma_f32_16x16x32_bf16 v[8:11], v[182:185], v[234:237], v[8:11]
	s_setprio 0
	s_setprio 1
	v_mfma_f32_16x16x32_bf16 v[52:55], v[186:189], v[202:205], v[52:55]
	v_mfma_f32_16x16x32_bf16 v[48:51], v[194:197], v[202:205], v[48:51]
	v_mfma_f32_16x16x32_bf16 v[36:39], v[186:189], v[210:213], v[36:39]
	v_mfma_f32_16x16x32_bf16 v[32:35], v[194:197], v[210:213], v[32:35]
	v_mfma_f32_16x16x32_bf16 v[20:23], v[186:189], v[218:221], v[20:23]
	v_mfma_f32_16x16x32_bf16 v[16:19], v[194:197], v[218:221], v[16:19]
	v_mfma_f32_16x16x32_bf16 v[4:7], v[186:189], v[230:233], v[4:7]
	v_mfma_f32_16x16x32_bf16 v[0:3], v[194:197], v[230:233], v[0:3]
	v_mfma_f32_16x16x32_bf16 v[52:55], v[190:193], v[206:209], v[52:55]
	v_mfma_f32_16x16x32_bf16 v[48:51], v[198:201], v[206:209], v[48:51]
	v_mfma_f32_16x16x32_bf16 v[36:39], v[190:193], v[214:217], v[36:39]
	v_mfma_f32_16x16x32_bf16 v[32:35], v[198:201], v[214:217], v[32:35]
	v_mfma_f32_16x16x32_bf16 v[20:23], v[190:193], v[222:225], v[20:23]
	v_mfma_f32_16x16x32_bf16 v[16:19], v[198:201], v[222:225], v[16:19]
	v_mfma_f32_16x16x32_bf16 v[4:7], v[190:193], v[234:237], v[4:7]
	v_mfma_f32_16x16x32_bf16 v[0:3], v[198:201], v[234:237], v[0:3]
	s_setprio 0
	s_barrier
	ds_read_b128 v[170:173], v168
	ds_read_b128 v[174:177], v168 offset:1024
	ds_read_b128 v[178:181], v168 offset:2048
	ds_read_b128 v[182:185], v168 offset:3072
	ds_read_b128 v[186:189], v169
	ds_read_b128 v[190:193], v169 offset:1024
	ds_read_b128 v[194:197], v169 offset:2048
	ds_read_b128 v[198:201], v169 offset:3072
	s_add_u32 s26, s26, 0x40000
	s_addc_u32 s27, s27, 0
	v_readfirstlane_b32 s43, v153
	v_lshl_add_u64 v[240:241], s[26:27], 0, v[128:129]
	s_mov_b32 m0, s43
	ds_read_b128 v[202:205], v165 offset:32768
	ds_read_b128 v[206:209], v165 offset:33792
	ds_read_b128 v[210:213], v165 offset:34816
	ds_read_b128 v[214:217], v165 offset:35840
	ds_read_b128 v[218:221], v165 offset:36864
	ds_read_b128 v[222:225], v165 offset:37888
	ds_read_b128 v[230:233], v165 offset:38912
	ds_read_b128 v[234:237], v165 offset:39936
	global_load_lds_dwordx4 v[240:241], off
	v_lshl_add_u64 v[240:241], s[26:27], 0, v[132:133]
	v_readfirstlane_b32 s26, v154
	s_mov_b32 m0, s26
	s_nop 0
	global_load_lds_dwordx4 v[240:241], off
	s_waitcnt vmcnt(8)
	s_waitcnt lgkmcnt(0)
	s_barrier
	s_setprio 1
	s_waitcnt lgkmcnt(0)
	v_mfma_f32_16x16x32_bf16 v[124:127], v[170:173], v[202:205], v[124:127]
	v_mfma_f32_16x16x32_bf16 v[120:123], v[178:181], v[202:205], v[120:123]
	v_mfma_f32_16x16x32_bf16 v[108:111], v[170:173], v[210:213], v[108:111]
	v_mfma_f32_16x16x32_bf16 v[104:107], v[178:181], v[210:213], v[104:107]
	v_mfma_f32_16x16x32_bf16 v[92:95], v[170:173], v[218:221], v[92:95]
	v_mfma_f32_16x16x32_bf16 v[88:91], v[178:181], v[218:221], v[88:91]
	v_mfma_f32_16x16x32_bf16 v[76:79], v[170:173], v[230:233], v[76:79]
	v_mfma_f32_16x16x32_bf16 v[72:75], v[178:181], v[230:233], v[72:75]
	v_mfma_f32_16x16x32_bf16 v[124:127], v[174:177], v[206:209], v[124:127]
	v_mfma_f32_16x16x32_bf16 v[120:123], v[182:185], v[206:209], v[120:123]
	v_mfma_f32_16x16x32_bf16 v[108:111], v[174:177], v[214:217], v[108:111]
	v_mfma_f32_16x16x32_bf16 v[104:107], v[182:185], v[214:217], v[104:107]
	v_mfma_f32_16x16x32_bf16 v[92:95], v[174:177], v[222:225], v[92:95]
	v_mfma_f32_16x16x32_bf16 v[88:91], v[182:185], v[222:225], v[88:91]
	v_mfma_f32_16x16x32_bf16 v[76:79], v[174:177], v[234:237], v[76:79]
	v_mfma_f32_16x16x32_bf16 v[72:75], v[182:185], v[234:237], v[72:75]
	s_setprio 0
	s_setprio 1
	v_mfma_f32_16x16x32_bf16 v[116:119], v[186:189], v[202:205], v[116:119]
	v_mfma_f32_16x16x32_bf16 v[112:115], v[194:197], v[202:205], v[112:115]
	v_mfma_f32_16x16x32_bf16 v[100:103], v[186:189], v[210:213], v[100:103]
	v_mfma_f32_16x16x32_bf16 v[96:99], v[194:197], v[210:213], v[96:99]
	v_mfma_f32_16x16x32_bf16 v[84:87], v[186:189], v[218:221], v[84:87]
	v_mfma_f32_16x16x32_bf16 v[80:83], v[194:197], v[218:221], v[80:83]
	v_mfma_f32_16x16x32_bf16 v[68:71], v[186:189], v[230:233], v[68:71]
	v_mfma_f32_16x16x32_bf16 v[64:67], v[194:197], v[230:233], v[64:67]
	v_mfma_f32_16x16x32_bf16 v[116:119], v[190:193], v[206:209], v[116:119]
	v_mfma_f32_16x16x32_bf16 v[112:115], v[198:201], v[206:209], v[112:115]
	v_mfma_f32_16x16x32_bf16 v[100:103], v[190:193], v[214:217], v[100:103]
	v_mfma_f32_16x16x32_bf16 v[96:99], v[198:201], v[214:217], v[96:99]
	v_mfma_f32_16x16x32_bf16 v[84:87], v[190:193], v[222:225], v[84:87]
	v_mfma_f32_16x16x32_bf16 v[80:83], v[198:201], v[222:225], v[80:83]
	v_mfma_f32_16x16x32_bf16 v[68:71], v[190:193], v[234:237], v[68:71]
	v_mfma_f32_16x16x32_bf16 v[64:67], v[198:201], v[234:237], v[64:67]
	s_setprio 0
	s_barrier
	v_readfirstlane_b32 s26, v155
	v_lshl_add_u64 v[144:145], v[144:145], 0, s[6:7]
	s_mov_b32 m0, s26
	v_readfirstlane_b32 s26, v156
	s_add_u32 s24, s24, 0x40080
	ds_read_b128 v[202:205], v165 offset:49152
	ds_read_b128 v[206:209], v165 offset:50176
	ds_read_b128 v[210:213], v165 offset:51200
	ds_read_b128 v[214:217], v165 offset:52224
	ds_read_b128 v[218:221], v165 offset:53248
	ds_read_b128 v[222:225], v165 offset:54272
	ds_read_b128 v[230:233], v165 offset:55296
	ds_read_b128 v[234:237], v165 offset:56320
	global_load_lds_dwordx4 v[144:145], off
	v_lshl_add_u64 v[144:145], v[226:227], 0, s[6:7]
	s_mov_b32 m0, s26
	s_addc_u32 s25, s25, 0
	v_readfirstlane_b32 s26, v159
	global_load_lds_dwordx4 v[144:145], off
	v_lshl_add_u64 v[144:145], s[24:25], 0, v[130:131]
	s_mov_b32 m0, s26
	s_nop 0
	global_load_lds_dwordx4 v[144:145], off
	v_lshl_add_u64 v[144:145], s[24:25], 0, v[134:135]
	v_readfirstlane_b32 s24, v160
	s_mov_b32 m0, s24
	v_readfirstlane_b32 s24, v157
	global_load_lds_dwordx4 v[144:145], off
	v_lshl_add_u64 v[144:145], v[228:229], 0, s[6:7]
	s_mov_b32 m0, s24
	v_readfirstlane_b32 s24, v158
	global_load_lds_dwordx4 v[144:145], off
	v_lshl_add_u64 v[144:145], v[238:239], 0, s[6:7]
	s_mov_b32 m0, s24
	s_nop 0
	global_load_lds_dwordx4 v[144:145], off
	s_waitcnt vmcnt(8)
	s_waitcnt lgkmcnt(0)
	s_barrier
	s_setprio 1
	s_waitcnt lgkmcnt(0)
	v_mfma_f32_16x16x32_bf16 v[60:63], v[170:173], v[202:205], v[60:63]
	v_mfma_f32_16x16x32_bf16 v[56:59], v[178:181], v[202:205], v[56:59]
	v_mfma_f32_16x16x32_bf16 v[44:47], v[170:173], v[210:213], v[44:47]
	v_mfma_f32_16x16x32_bf16 v[40:43], v[178:181], v[210:213], v[40:43]
	v_mfma_f32_16x16x32_bf16 v[28:31], v[170:173], v[218:221], v[28:31]
	v_mfma_f32_16x16x32_bf16 v[24:27], v[178:181], v[218:221], v[24:27]
	v_mfma_f32_16x16x32_bf16 v[12:15], v[170:173], v[230:233], v[12:15]
	v_mfma_f32_16x16x32_bf16 v[8:11], v[178:181], v[230:233], v[8:11]
	v_mfma_f32_16x16x32_bf16 v[60:63], v[174:177], v[206:209], v[60:63]
	v_mfma_f32_16x16x32_bf16 v[56:59], v[182:185], v[206:209], v[56:59]
	v_mfma_f32_16x16x32_bf16 v[44:47], v[174:177], v[214:217], v[44:47]
	v_mfma_f32_16x16x32_bf16 v[40:43], v[182:185], v[214:217], v[40:43]
	v_mfma_f32_16x16x32_bf16 v[28:31], v[174:177], v[222:225], v[28:31]
	v_mfma_f32_16x16x32_bf16 v[24:27], v[182:185], v[222:225], v[24:27]
	v_mfma_f32_16x16x32_bf16 v[12:15], v[174:177], v[234:237], v[12:15]
	v_mfma_f32_16x16x32_bf16 v[8:11], v[182:185], v[234:237], v[8:11]
	s_setprio 0
	s_setprio 1
	v_mfma_f32_16x16x32_bf16 v[52:55], v[186:189], v[202:205], v[52:55]
	v_mfma_f32_16x16x32_bf16 v[48:51], v[194:197], v[202:205], v[48:51]
	v_mfma_f32_16x16x32_bf16 v[36:39], v[186:189], v[210:213], v[36:39]
	v_mfma_f32_16x16x32_bf16 v[32:35], v[194:197], v[210:213], v[32:35]
	v_mfma_f32_16x16x32_bf16 v[20:23], v[186:189], v[218:221], v[20:23]
	v_mfma_f32_16x16x32_bf16 v[16:19], v[194:197], v[218:221], v[16:19]
	v_mfma_f32_16x16x32_bf16 v[4:7], v[186:189], v[230:233], v[4:7]
	v_mfma_f32_16x16x32_bf16 v[0:3], v[194:197], v[230:233], v[0:3]
	v_mfma_f32_16x16x32_bf16 v[52:55], v[190:193], v[206:209], v[52:55]
	v_mfma_f32_16x16x32_bf16 v[48:51], v[198:201], v[206:209], v[48:51]
	v_mfma_f32_16x16x32_bf16 v[36:39], v[190:193], v[214:217], v[36:39]
	v_mfma_f32_16x16x32_bf16 v[32:35], v[198:201], v[214:217], v[32:35]
	v_mfma_f32_16x16x32_bf16 v[20:23], v[190:193], v[222:225], v[20:23]
	v_mfma_f32_16x16x32_bf16 v[16:19], v[198:201], v[222:225], v[16:19]
	v_mfma_f32_16x16x32_bf16 v[4:7], v[190:193], v[234:237], v[4:7]
	v_mfma_f32_16x16x32_bf16 v[0:3], v[198:201], v[234:237], v[0:3]
	s_setprio 0
	s_barrier
	s_add_i32 s42, s42, 2
	s_add_u32 s22, s22, 0x100
	s_addc_u32 s23, s23, 0
	s_add_u32 s40, s40, 0x100
	s_addc_u32 s41, s41, 0
	s_cmp_gt_u32 s42, 13
	s_cbranch_scc0 .LBB0_2729
	s_add_u32 s100, s38, 0x40080
	s_addc_u32 s101, s15, 0
	v_readfirstlane_b32 s43, v166
	v_lshl_add_u64 v[144:145], s[100:101], 0, v[136:137]
	s_mov_b32 m0, s43
	v_readfirstlane_b32 s43, v167
	global_load_lds_dwordx4 v[144:145], off
	v_lshl_add_u64 v[144:145], s[100:101], 0, v[138:139]
	s_mov_b32 m0, s43
	s_nop 0
	global_load_lds_dwordx4 v[144:145], off
	s_and_b64 vcc, exec, s[8:9]
	s_cbranch_vccz .LBB0_2732
	s_barrier
